# LN1/LN2: batched the row loads (unique dst regs, one counted vmcnt ladder) instead of 16 serialized load-wait round trips; attention read-before-DMA order
# speedup vs baseline: 1.0178x; 1.0135x over previous
; __device__ __forceinline__ float bflo(unsigned w) { return __uint_as_float(w << 16); }
; __device__ __forceinline__ float bfhi(unsigned w) { return __uint_as_float(w & 0xffff0000u); }
; __global__ void __launch_bounds__(NWAVES * 64, 2) mega_fwd(Args args) {
;     ...
;         for (int row = gw; row < TOK; row += NGW) {
;             const float* xr = xin + (size_t)row * DM; const bf16* mr = MP + (size_t)row * DM; f32x4 v[16]; float s = 0.f;
; #pragma unroll
;             for (int j = 0; j < 16; ++j) { const f32x4 xv = *(const f32x4*)(xr + 4 * lane + 256 * j); const v2u m = *(const v2u*)(mr + 4 * lane + 256 * j);
;                 v[j] = xv * DEEP_ALPHA + (f32x4){bflo(m[0]), bfhi(m[0]), bflo(m[1]), bfhi(m[1])}; s += (v[j][0] + v[j][1]) + (v[j][2] + v[j][3]); }
.LBB0_506:
	v_add_co_u32_e32 v76, vcc, 0xffffd000, v64
	v_lshl_add_u64 v[66:67], s[78:79], 0, v[62:63]
	s_nop 0
	v_addc_co_u32_e32 v77, vcc, -1, v65, vcc
	v_add_co_u32_e32 v0, vcc, 0x38e00000, v66
	global_load_dwordx4 v[142:145], v[76:77], off offset:-3072
	s_nop 0
	v_addc_co_u32_e32 v1, vcc, 0, v67, vcc
	global_load_dwordx2 v[146:147], v[0:1], off
	s_movk_i32 s5, 0xe000
	v_add_co_u32_e32 v96, vcc, s5, v64
	s_movk_i32 s5, 0xf000
	s_nop 0
	v_addc_co_u32_e32 v97, vcc, -1, v65, vcc
	v_add_co_u32_e32 v106, vcc, s5, v64
	s_mov_b32 s5, 0x38e01000
	s_nop 0
	v_addc_co_u32_e32 v107, vcc, -1, v65, vcc
	v_add_co_u32_e32 v124, vcc, s5, v66
	s_nop 1
	v_addc_co_u32_e32 v125, vcc, 0, v67, vcc
	global_load_dwordx4 v[148:151], v[76:77], off offset:-2048
	global_load_dwordx2 v[152:153], v[0:1], off offset:512
	s_nop 0
	global_load_dwordx4 v[154:157], v[76:77], off offset:-1024
	global_load_dwordx2 v[158:159], v[0:1], off offset:1024
	global_load_dwordx4 v[160:163], v[76:77], off
	s_nop 0
	global_load_dwordx2 v[164:165], v[0:1], off offset:1536
	s_nop 0
	global_load_dwordx4 v[166:169], v[96:97], off offset:-3072
	global_load_dwordx2 v[170:171], v[0:1], off offset:2048
	s_nop 0
	global_load_dwordx4 v[172:175], v[96:97], off offset:-2048
	global_load_dwordx2 v[176:177], v[0:1], off offset:2560
	global_load_dwordx4 v[178:181], v[96:97], off offset:-1024
	global_load_dwordx2 v[182:183], v[0:1], off offset:3072
	global_load_dwordx4 v[184:187], v[96:97], off
	s_nop 0
	global_load_dwordx2 v[188:189], v[0:1], off offset:3584
	global_load_dwordx2 v[190:191], v[124:125], off
	global_load_dwordx4 v[194:197], v[106:107], off offset:-3072
	global_load_dwordx4 v[198:201], v[106:107], off offset:-2048
	global_load_dwordx2 v[202:203], v[124:125], off offset:512
	s_nop 0
	s_nop 0
	global_load_dwordx4 v[204:207], v[106:107], off offset:-1024
	global_load_dwordx2 v[208:209], v[124:125], off offset:1024
	s_nop 0
	global_load_dwordx4 v[210:213], v[64:65], off offset:-4096
	global_load_dwordx2 v[214:215], v[124:125], off offset:1536
	global_load_dwordx4 v[220:223], v[64:65], off offset:-3072
	global_load_dwordx2 v[224:225], v[124:125], off offset:2048
	s_nop 0
	s_nop 0
	global_load_dwordx4 v[226:229], v[64:65], off offset:-2048
	global_load_dwordx2 v[230:231], v[124:125], off offset:2560
	s_nop 0
	global_load_dwordx4 v[232:235], v[64:65], off offset:-1024
	global_load_dwordx2 v[236:237], v[124:125], off offset:3072
	global_load_dwordx4 v[238:241], v[64:65], off
	s_nop 0
	global_load_dwordx2 v[242:243], v[124:125], off offset:3584
	s_mov_b32 s5, 0xda24260
	s_nop 1
	s_waitcnt vmcnt(30)
	v_lshlrev_b32_e32 v68, 16, v146
	v_and_b32_e32 v69, 0xffff0000, v146
	v_lshlrev_b32_e32 v6, 16, v147
	v_and_b32_e32 v7, 0xffff0000, v147
	v_pk_fma_f32 v[4:5], v[144:145], s[88:89], v[6:7] op_sel_hi:[1,0,1]
	v_pk_fma_f32 v[6:7], v[142:143], s[88:89], v[68:69] op_sel_hi:[1,0,1]
	v_mov_b32_e32 v69, v5
	v_pk_mov_b32 v[2:3], v[6:7], v[4:5] op_sel:[1,0]
	v_mov_b32_e32 v68, v6
	v_pk_add_f32 v[2:3], v[2:3], v[68:69]
	s_nop 1
	v_add_f32_e32 v2, v2, v3
	v_add_f32_e32 v2, 0, v2
	s_waitcnt vmcnt(28)
	v_lshlrev_b32_e32 v74, 16, v152
	v_and_b32_e32 v75, 0xffff0000, v152
	v_lshlrev_b32_e32 v72, 16, v153
	v_and_b32_e32 v73, 0xffff0000, v153
	v_pk_fma_f32 v[72:73], v[150:151], s[88:89], v[72:73] op_sel_hi:[1,0,1]
	v_pk_fma_f32 v[74:75], v[148:149], s[88:89], v[74:75] op_sel_hi:[1,0,1]
	v_mov_b32_e32 v71, v73
	v_pk_mov_b32 v[68:69], v[74:75], v[72:73] op_sel:[1,0]
	v_mov_b32_e32 v70, v74
	v_pk_add_f32 v[68:69], v[68:69], v[70:71]
	s_nop 0
	v_pk_add_f32 v[84:85], v[68:69], v[68:69] op_sel:[0,1] op_sel_hi:[1,0]
	s_nop 1
	s_waitcnt vmcnt(26)
	v_lshlrev_b32_e32 v80, 16, v158
	v_and_b32_e32 v81, 0xffff0000, v158
	v_lshlrev_b32_e32 v78, 16, v159
	v_and_b32_e32 v79, 0xffff0000, v159
	v_pk_fma_f32 v[78:79], v[156:157], s[88:89], v[78:79] op_sel_hi:[1,0,1]
	v_pk_fma_f32 v[82:83], v[154:155], s[88:89], v[80:81] op_sel_hi:[1,0,1]
	s_nop 1
	v_add_f32_e32 v86, v82, v83
	v_add_f32_e32 v88, v78, v79
	s_waitcnt vmcnt(24)
	v_lshlrev_b32_e32 v80, 16, v164
	v_and_b32_e32 v81, 0xffff0000, v164
	v_lshlrev_b32_e32 v76, 16, v165
	v_and_b32_e32 v77, 0xffff0000, v165
	v_pk_fma_f32 v[76:77], v[162:163], s[88:89], v[76:77] op_sel_hi:[1,0,1]
	v_pk_fma_f32 v[80:81], v[160:161], s[88:89], v[80:81] op_sel_hi:[1,0,1]
	v_mov_b32_e32 v87, v76
	v_mov_b32_e32 v3, v80
	v_mov_b32_e32 v85, v81
	v_mov_b32_e32 v89, v77
	v_pk_add_f32 v[2:3], v[2:3], v[84:85]
	v_pk_add_f32 v[68:69], v[86:87], v[88:89]
	s_nop 0
	v_pk_add_f32 v[2:3], v[2:3], v[68:69]
	s_nop 1
	v_pk_add_f32 v[2:3], v[2:3], v[2:3] op_sel:[0,1] op_sel_hi:[1,0]
	s_waitcnt vmcnt(22)
	v_lshlrev_b32_e32 v86, 16, v170
	v_and_b32_e32 v87, 0xffff0000, v170
	v_lshlrev_b32_e32 v84, 16, v171
	v_and_b32_e32 v85, 0xffff0000, v171
	v_pk_fma_f32 v[88:89], v[168:169], s[88:89], v[84:85] op_sel_hi:[1,0,1]
	v_pk_fma_f32 v[90:91], v[166:167], s[88:89], v[86:87] op_sel_hi:[1,0,1]
	v_mov_b32_e32 v71, v89
	v_pk_mov_b32 v[68:69], v[90:91], v[88:89] op_sel:[1,0]
	v_mov_b32_e32 v70, v90
	v_pk_add_f32 v[68:69], v[68:69], v[70:71]
	s_nop 0
	v_pk_add_f32 v[98:99], v[68:69], v[68:69] op_sel:[0,1] op_sel_hi:[1,0]
	s_nop 1
	s_waitcnt vmcnt(20)
	v_lshlrev_b32_e32 v86, 16, v176
	v_and_b32_e32 v87, 0xffff0000, v176
	v_lshlrev_b32_e32 v84, 16, v177
	v_and_b32_e32 v85, 0xffff0000, v177
	v_pk_fma_f32 v[92:93], v[174:175], s[88:89], v[84:85] op_sel_hi:[1,0,1]
	v_pk_fma_f32 v[94:95], v[172:173], s[88:89], v[86:87] op_sel_hi:[1,0,1]
	s_nop 1
	v_add_f32_e32 v100, v94, v95
	v_add_f32_e32 v102, v92, v93
	s_waitcnt vmcnt(18)
; __device__ __forceinline__ float bflo(unsigned w) { return __uint_as_float(w << 16); }
; __device__ __forceinline__ float bfhi(unsigned w) { return __uint_as_float(w & 0xffff0000u); }
; __global__ void __launch_bounds__(NWAVES * 64, 2) mega_fwd(Args args) {
;     ...
;             for (int j = 0; j < 16; ++j) { const f32x4 xv = *(const f32x4*)(xr + 4 * lane + 256 * j); const v2u m = *(const v2u*)(mr + 4 * lane + 256 * j);
;                 v[j] = xv * DEEP_ALPHA + (f32x4){bflo(m[0]), bfhi(m[0]), bflo(m[1]), bfhi(m[1])}; s += (v[j][0] + v[j][1]) + (v[j][2] + v[j][3]); }
;             const float mean = wave_sum(s, lane) * (1.0f / DM); float q = 0.f;
	v_lshlrev_b32_e32 v86, 16, v182
	v_and_b32_e32 v87, 0xffff0000, v182
	v_pk_fma_f32 v[86:87], v[178:179], s[88:89], v[86:87] op_sel_hi:[1,0,1]
	v_lshlrev_b32_e32 v84, 16, v183
	v_mov_b32_e32 v3, v86
	v_mov_b32_e32 v99, v87
	v_pk_add_f32 v[2:3], v[2:3], v[98:99]
	s_nop 1
	v_and_b32_e32 v85, 0xffff0000, v183
	v_pk_fma_f32 v[84:85], v[180:181], s[88:89], v[84:85] op_sel_hi:[1,0,1]
	s_waitcnt vmcnt(16)
	v_lshlrev_b32_e32 v70, 16, v188
	v_mov_b32_e32 v101, v84
	v_mov_b32_e32 v103, v85
	v_pk_add_f32 v[68:69], v[100:101], v[102:103]
	v_and_b32_e32 v71, 0xffff0000, v188
	v_lshlrev_b32_e32 v0, 16, v189
	v_and_b32_e32 v1, 0xffff0000, v189
	v_pk_add_f32 v[2:3], v[2:3], v[68:69]
	v_pk_fma_f32 v[68:69], v[186:187], s[88:89], v[0:1] op_sel_hi:[1,0,1]
	v_pk_fma_f32 v[70:71], v[184:185], s[88:89], v[70:71] op_sel_hi:[1,0,1]
	v_mov_b32_e32 v97, v69
	v_pk_mov_b32 v[0:1], v[70:71], v[68:69] op_sel:[1,0]
	v_mov_b32_e32 v96, v70
	v_pk_add_f32 v[0:1], v[0:1], v[96:97]
	s_nop 1
	v_pk_add_f32 v[2:3], v[2:3], v[2:3] op_sel:[0,1] op_sel_hi:[1,0]
	v_pk_add_f32 v[0:1], v[0:1], v[0:1] op_sel:[0,1] op_sel_hi:[1,0]
	s_waitcnt vmcnt(15)
	v_lshlrev_b32_e32 v102, 16, v190
	v_and_b32_e32 v103, 0xffff0000, v190
	v_lshlrev_b32_e32 v96, 16, v191
	v_and_b32_e32 v97, 0xffff0000, v191
	s_waitcnt vmcnt(14)
	v_pk_fma_f32 v[96:97], v[196:197], s[88:89], v[96:97] op_sel_hi:[1,0,1]
	v_pk_fma_f32 v[98:99], v[194:195], s[88:89], v[102:103] op_sel_hi:[1,0,1]
	s_nop 1
	v_add_f32_e32 v108, v98, v99
	v_add_f32_e32 v110, v96, v97
	s_waitcnt vmcnt(12)
	v_lshlrev_b32_e32 v112, 16, v202
	v_and_b32_e32 v113, 0xffff0000, v202
	v_lshlrev_b32_e32 v100, 16, v203
	v_and_b32_e32 v101, 0xffff0000, v203
	v_pk_fma_f32 v[100:101], v[200:201], s[88:89], v[100:101] op_sel_hi:[1,0,1]
	v_pk_fma_f32 v[102:103], v[198:199], s[88:89], v[112:113] op_sel_hi:[1,0,1]
	v_mov_b32_e32 v109, v100
	v_mov_b32_e32 v3, v102
	v_mov_b32_e32 v1, v103
	v_mov_b32_e32 v111, v101
	v_pk_add_f32 v[0:1], v[2:3], v[0:1]
	v_pk_add_f32 v[2:3], v[108:109], v[110:111]
	s_nop 0
	v_pk_add_f32 v[0:1], v[0:1], v[2:3]
	s_nop 0
	v_pk_add_f32 v[116:117], v[0:1], v[0:1] op_sel:[0,1] op_sel_hi:[1,0]
	s_nop 1
	s_waitcnt vmcnt(10)
	v_lshlrev_b32_e32 v106, 16, v208
	v_and_b32_e32 v107, 0xffff0000, v208
	v_lshlrev_b32_e32 v104, 16, v209
	v_and_b32_e32 v105, 0xffff0000, v209
	v_pk_fma_f32 v[104:105], v[206:207], s[88:89], v[104:105] op_sel_hi:[1,0,1]
	v_pk_fma_f32 v[106:107], v[204:205], s[88:89], v[106:107] op_sel_hi:[1,0,1]
	v_mov_b32_e32 v3, v105
	v_pk_mov_b32 v[0:1], v[106:107], v[104:105] op_sel:[1,0]
	v_mov_b32_e32 v2, v106
	v_pk_add_f32 v[0:1], v[0:1], v[2:3]
	s_nop 0
	v_pk_add_f32 v[118:119], v[0:1], v[0:1] op_sel:[0,1] op_sel_hi:[1,0]
	s_nop 1
	s_waitcnt vmcnt(8)
	v_lshlrev_b32_e32 v110, 16, v214
	v_and_b32_e32 v111, 0xffff0000, v214
	v_lshlrev_b32_e32 v108, 16, v215
	v_and_b32_e32 v109, 0xffff0000, v215
	v_pk_fma_f32 v[108:109], v[212:213], s[88:89], v[108:109] op_sel_hi:[1,0,1]
	v_pk_fma_f32 v[110:111], v[210:211], s[88:89], v[110:111] op_sel_hi:[1,0,1]
	s_nop 1
	v_add_f32_e32 v120, v110, v111
	v_add_f32_e32 v122, v108, v109
	s_waitcnt vmcnt(6)
	v_lshlrev_b32_e32 v114, 16, v224
	v_and_b32_e32 v115, 0xffff0000, v224
	v_lshlrev_b32_e32 v112, 16, v225
	v_and_b32_e32 v113, 0xffff0000, v225
	v_pk_fma_f32 v[112:113], v[222:223], s[88:89], v[112:113] op_sel_hi:[1,0,1]
	v_pk_fma_f32 v[114:115], v[220:221], s[88:89], v[114:115] op_sel_hi:[1,0,1]
	v_mov_b32_e32 v121, v112
	v_mov_b32_e32 v117, v114
	v_mov_b32_e32 v119, v115
	v_mov_b32_e32 v123, v113
	v_pk_add_f32 v[0:1], v[116:117], v[118:119]
	v_pk_add_f32 v[2:3], v[120:121], v[122:123]
	s_nop 0
	v_pk_add_f32 v[0:1], v[0:1], v[2:3]
	s_nop 0
	v_pk_add_f32 v[128:129], v[0:1], v[0:1] op_sel:[0,1] op_sel_hi:[1,0]
	s_nop 1
	s_waitcnt vmcnt(4)
	v_lshlrev_b32_e32 v118, 16, v230
	v_and_b32_e32 v119, 0xffff0000, v230
	v_lshlrev_b32_e32 v116, 16, v231
	v_and_b32_e32 v117, 0xffff0000, v231
	v_pk_fma_f32 v[116:117], v[228:229], s[88:89], v[116:117] op_sel_hi:[1,0,1]
	v_pk_fma_f32 v[118:119], v[226:227], s[88:89], v[118:119] op_sel_hi:[1,0,1]
	v_mov_b32_e32 v3, v117
	v_pk_mov_b32 v[0:1], v[118:119], v[116:117] op_sel:[1,0]
	v_mov_b32_e32 v2, v118
	v_pk_add_f32 v[0:1], v[0:1], v[2:3]
	s_nop 0
	v_pk_add_f32 v[130:131], v[0:1], v[0:1] op_sel:[0,1] op_sel_hi:[1,0]
	s_nop 1
	s_waitcnt vmcnt(2)
	v_lshlrev_b32_e32 v122, 16, v236
	v_and_b32_e32 v123, 0xffff0000, v236
	v_lshlrev_b32_e32 v120, 16, v237
	v_and_b32_e32 v121, 0xffff0000, v237
	v_pk_fma_f32 v[120:121], v[234:235], s[88:89], v[120:121] op_sel_hi:[1,0,1]
	v_pk_fma_f32 v[122:123], v[232:233], s[88:89], v[122:123] op_sel_hi:[1,0,1]
	s_nop 1
	v_add_f32_e32 v132, v122, v123
	v_add_f32_e32 v134, v120, v121
	s_waitcnt vmcnt(0)
	v_lshlrev_b32_e32 v126, 16, v242
	v_and_b32_e32 v127, 0xffff0000, v242
	v_lshlrev_b32_e32 v124, 16, v243
	v_and_b32_e32 v125, 0xffff0000, v243
	v_pk_fma_f32 v[124:125], v[240:241], s[88:89], v[124:125] op_sel_hi:[1,0,1]
	v_pk_fma_f32 v[126:127], v[238:239], s[88:89], v[126:127] op_sel_hi:[1,0,1]
	v_mov_b32_e32 v133, v124
	v_mov_b32_e32 v129, v126
	v_mov_b32_e32 v131, v127
	v_mov_b32_e32 v135, v125
	v_pk_add_f32 v[0:1], v[128:129], v[130:131]
	v_pk_add_f32 v[2:3], v[132:133], v[134:135]
	s_nop 0
	v_pk_add_f32 v[0:1], v[0:1], v[2:3]
	s_nop 0
	v_add_f32_e32 v0, v0, v1
	ds_bpermute_b32 v1, v136, v0
	s_waitcnt lgkmcnt(0)
	v_add_f32_e32 v0, v0, v1
	ds_bpermute_b32 v1, v137, v0
	s_waitcnt lgkmcnt(0)
	v_add_f32_e32 v0, v0, v1
	ds_bpermute_b32 v1, v138, v0
	s_waitcnt lgkmcnt(0)
	v_add_f32_e32 v0, v0, v1
	ds_bpermute_b32 v1, v139, v0
	s_waitcnt lgkmcnt(0)
	v_add_f32_e32 v0, v0, v1
	ds_bpermute_b32 v1, v140, v0
	s_waitcnt lgkmcnt(0)
; __global__ void __launch_bounds__(NWAVES * 64, 2) mega_fwd(Args args) {
;     ...
;             const float mean = wave_sum(s, lane) * (1.0f / DM); float q = 0.f;
; #pragma unroll
;             for (int j = 0; j < 16; ++j) { v[j] = v[j] - mean; q += (v[j][0] * v[j][0] + v[j][1] * v[j][1]) + (v[j][2] * v[j][2] + v[j][3] * v[j][3]); }
	v_add_f32_e32 v0, v0, v1
	ds_bpermute_b32 v1, v141, v0
	s_waitcnt lgkmcnt(0)
	v_add_f32_e32 v132, v0, v1
	v_fmamk_f32 v7, v132, 0xb9800000, v7
	v_fmac_f32_e32 v6, 0xb9800000, v132
	v_fmamk_f32 v5, v132, 0xb9800000, v5
	v_fmac_f32_e32 v4, 0xb9800000, v132
	v_pk_mul_f32 v[0:1], v[4:5], v[4:5]
	v_pk_mul_f32 v[2:3], v[6:7], v[6:7]
	v_fmamk_f32 v75, v132, 0xb9800000, v75
	v_pk_mov_b32 v[128:129], v[2:3], v[0:1] op_sel:[1,0]
	v_mov_b32_e32 v3, v1
	v_fmac_f32_e32 v74, 0xb9800000, v132
	v_fmamk_f32 v73, v132, 0xb9800000, v73
	v_fmac_f32_e32 v72, 0xb9800000, v132
	v_pk_add_f32 v[0:1], v[128:129], v[2:3]
	v_pk_mul_f32 v[2:3], v[72:73], v[72:73]
	v_pk_mul_f32 v[128:129], v[74:75], v[74:75]
	v_fmamk_f32 v81, v132, 0xb9800000, v81
	v_pk_mov_b32 v[130:131], v[128:129], v[2:3] op_sel:[1,0]
	v_mov_b32_e32 v129, v3
	v_pk_add_f32 v[2:3], v[130:131], v[128:129]
	v_fmac_f32_e32 v80, 0xb9800000, v132
	v_mul_f32_e32 v128, v80, v80
	v_mul_f32_e32 v129, v81, v81
	v_pk_add_f32 v[0:1], v[0:1], v[0:1] op_sel:[0,1] op_sel_hi:[1,0]
	v_pk_add_f32 v[2:3], v[2:3], v[2:3] op_sel:[0,1] op_sel_hi:[1,0]
	v_fmamk_f32 v83, v132, 0xb9800000, v83
	v_fmamk_f32 v79, v132, 0xb9800000, v79
	v_mov_b32_e32 v1, v128
	v_mov_b32_e32 v3, v129
	v_fmac_f32_e32 v82, 0xb9800000, v132
	v_fmac_f32_e32 v78, 0xb9800000, v132
	v_fmamk_f32 v77, v132, 0xb9800000, v77
	v_fmac_f32_e32 v76, 0xb9800000, v132
	v_pk_add_f32 v[0:1], v[0:1], v[2:3]
	v_mul_f32_e32 v2, v83, v83
	v_mul_f32_e32 v128, v79, v79
	v_mul_f32_e32 v130, v76, v76
	v_mul_f32_e32 v131, v77, v77
	v_pk_fma_f32 v[2:3], v[82:83], v[82:83], v[2:3] op_sel_hi:[1,1,0]
	v_pk_fma_f32 v[128:129], v[78:79], v[78:79], v[128:129] op_sel_hi:[1,1,0]
	v_mov_b32_e32 v3, v130
	v_mov_b32_e32 v129, v131
	v_pk_add_f32 v[2:3], v[2:3], v[128:129]
	v_fmamk_f32 v91, v132, 0xb9800000, v91
	v_fmac_f32_e32 v90, 0xb9800000, v132
	v_fmamk_f32 v89, v132, 0xb9800000, v89
	v_fmac_f32_e32 v88, 0xb9800000, v132
	v_pk_add_f32 v[0:1], v[0:1], v[2:3]
	v_pk_mul_f32 v[2:3], v[88:89], v[88:89]
	v_pk_mul_f32 v[128:129], v[90:91], v[90:91]
	v_fmamk_f32 v87, v132, 0xb9800000, v87
	v_pk_mov_b32 v[130:131], v[128:129], v[2:3] op_sel:[1,0]
	v_mov_b32_e32 v129, v3
	v_pk_add_f32 v[2:3], v[130:131], v[128:129]
	v_fmac_f32_e32 v86, 0xb9800000, v132
	v_mul_f32_e32 v128, v86, v86
	v_mul_f32_e32 v129, v87, v87
	v_pk_add_f32 v[0:1], v[0:1], v[0:1] op_sel:[0,1] op_sel_hi:[1,0]
	v_pk_add_f32 v[2:3], v[2:3], v[2:3] op_sel:[0,1] op_sel_hi:[1,0]
	v_fmamk_f32 v95, v132, 0xb9800000, v95
	v_fmamk_f32 v93, v132, 0xb9800000, v93
	v_mov_b32_e32 v1, v128
	v_mov_b32_e32 v3, v129
	v_fmac_f32_e32 v94, 0xb9800000, v132
	v_fmac_f32_e32 v92, 0xb9800000, v132
	v_fmamk_f32 v85, v132, 0xb9800000, v85
	v_fmac_f32_e32 v84, 0xb9800000, v132
	v_pk_add_f32 v[0:1], v[0:1], v[2:3]
	v_mul_f32_e32 v2, v95, v95
	v_mul_f32_e32 v128, v93, v93
	v_mul_f32_e32 v130, v84, v84
	v_mul_f32_e32 v131, v85, v85
	v_pk_fma_f32 v[2:3], v[94:95], v[94:95], v[2:3] op_sel_hi:[1,1,0]
	v_pk_fma_f32 v[128:129], v[92:93], v[92:93], v[128:129] op_sel_hi:[1,1,0]
	v_mov_b32_e32 v3, v130
	v_mov_b32_e32 v129, v131
	v_pk_add_f32 v[2:3], v[2:3], v[128:129]
	v_fmamk_f32 v71, v132, 0xb9800000, v71
	v_fmac_f32_e32 v70, 0xb9800000, v132
	v_fmamk_f32 v69, v132, 0xb9800000, v69
	v_fmac_f32_e32 v68, 0xb9800000, v132
	v_pk_add_f32 v[0:1], v[0:1], v[2:3]
	v_pk_mul_f32 v[2:3], v[68:69], v[68:69]
	v_pk_mul_f32 v[128:129], v[70:71], v[70:71]
	v_fmamk_f32 v103, v132, 0xb9800000, v103
	v_pk_mov_b32 v[130:131], v[128:129], v[2:3] op_sel:[1,0]
	v_mov_b32_e32 v129, v3
	v_pk_add_f32 v[2:3], v[130:131], v[128:129]
	v_fmac_f32_e32 v102, 0xb9800000, v132
	v_mul_f32_e32 v128, v102, v102
	v_mul_f32_e32 v129, v103, v103
	v_pk_add_f32 v[0:1], v[0:1], v[0:1] op_sel:[0,1] op_sel_hi:[1,0]
	v_pk_add_f32 v[2:3], v[2:3], v[2:3] op_sel:[0,1] op_sel_hi:[1,0]
	v_fmamk_f32 v99, v132, 0xb9800000, v99
	v_fmamk_f32 v97, v132, 0xb9800000, v97
	v_mov_b32_e32 v1, v128
	v_mov_b32_e32 v3, v129
	v_fmac_f32_e32 v98, 0xb9800000, v132
	v_fmac_f32_e32 v96, 0xb9800000, v132
	v_fmamk_f32 v101, v132, 0xb9800000, v101
	v_fmac_f32_e32 v100, 0xb9800000, v132
	v_pk_add_f32 v[0:1], v[0:1], v[2:3]
	v_mul_f32_e32 v2, v99, v99
	v_mul_f32_e32 v128, v97, v97
	v_mul_f32_e32 v130, v100, v100
	v_mul_f32_e32 v131, v101, v101
	v_pk_fma_f32 v[2:3], v[98:99], v[98:99], v[2:3] op_sel_hi:[1,1,0]
	v_pk_fma_f32 v[128:129], v[96:97], v[96:97], v[128:129] op_sel_hi:[1,1,0]
	v_mov_b32_e32 v3, v130
	v_mov_b32_e32 v129, v131
	v_pk_add_f32 v[2:3], v[2:3], v[128:129]
	v_fmamk_f32 v107, v132, 0xb9800000, v107
	v_fmac_f32_e32 v106, 0xb9800000, v132
	v_fmamk_f32 v105, v132, 0xb9800000, v105
	v_fmac_f32_e32 v104, 0xb9800000, v132
	v_pk_add_f32 v[0:1], v[0:1], v[2:3]
	v_pk_mul_f32 v[2:3], v[104:105], v[104:105]
	v_pk_mul_f32 v[128:129], v[106:107], v[106:107]
	v_fmamk_f32 v115, v132, 0xb9800000, v115
	v_pk_mov_b32 v[130:131], v[128:129], v[2:3] op_sel:[1,0]
	v_mov_b32_e32 v129, v3
	v_pk_add_f32 v[2:3], v[130:131], v[128:129]
	v_fmac_f32_e32 v114, 0xb9800000, v132
	v_mul_f32_e32 v128, v114, v114
	v_mul_f32_e32 v129, v115, v115
	v_pk_add_f32 v[0:1], v[0:1], v[0:1] op_sel:[0,1] op_sel_hi:[1,0]
	v_pk_add_f32 v[2:3], v[2:3], v[2:3] op_sel:[0,1] op_sel_hi:[1,0]
	v_fmamk_f32 v111, v132, 0xb9800000, v111
	v_fmamk_f32 v109, v132, 0xb9800000, v109
	v_mov_b32_e32 v1, v128
	v_mov_b32_e32 v3, v129
	v_fmac_f32_e32 v110, 0xb9800000, v132
	v_fmac_f32_e32 v108, 0xb9800000, v132
	v_fmamk_f32 v113, v132, 0xb9800000, v113
	v_fmac_f32_e32 v112, 0xb9800000, v132
	v_pk_add_f32 v[0:1], v[0:1], v[2:3]
	v_mul_f32_e32 v2, v111, v111
	v_mul_f32_e32 v128, v109, v109
	v_mul_f32_e32 v130, v112, v112
	v_mul_f32_e32 v131, v113, v113
; __global__ void __launch_bounds__(NWAVES * 64, 2) mega_fwd(Args args) {
;     ...
;             for (int j = 0; j < 16; ++j) { v[j] = v[j] - mean; q += (v[j][0] * v[j][0] + v[j][1] * v[j][1]) + (v[j][2] * v[j][2] + v[j][3] * v[j][3]); }
;             const float rstd = 1.0f / sqrtf(wave_sum(q, lane) * (1.0f / DM) + LN_EPS); float am = 0.f;
; #pragma unroll
;             for (int j = 0; j < 16; ++j) { const f32x4 gg = *(const f32x4*)(ln1_g + 4 * lane + 256 * j), bb = *(const f32x4*)(ln1_b + 4 * lane + 256 * j);
;                 const f32x4 y = v[j] * rstd * gg + bb; v[j] = y; am = fmaxf(fmaxf(am, fmaxf(fabsf(y[0]), fabsf(y[1]))), fmaxf(fabsf(y[2]), fabsf(y[3]))); }
	v_pk_fma_f32 v[2:3], v[110:111], v[110:111], v[2:3] op_sel_hi:[1,1,0]
	v_pk_fma_f32 v[128:129], v[108:109], v[108:109], v[128:129] op_sel_hi:[1,1,0]
	v_mov_b32_e32 v3, v130
	v_mov_b32_e32 v129, v131
	v_pk_add_f32 v[2:3], v[2:3], v[128:129]
	v_fmamk_f32 v119, v132, 0xb9800000, v119
	v_fmac_f32_e32 v118, 0xb9800000, v132
	v_fmamk_f32 v117, v132, 0xb9800000, v117
	v_fmac_f32_e32 v116, 0xb9800000, v132
	v_pk_add_f32 v[0:1], v[0:1], v[2:3]
	v_pk_mul_f32 v[2:3], v[116:117], v[116:117]
	v_pk_mul_f32 v[128:129], v[118:119], v[118:119]
	v_fmamk_f32 v127, v132, 0xb9800000, v127
	v_pk_mov_b32 v[130:131], v[128:129], v[2:3] op_sel:[1,0]
	v_mov_b32_e32 v129, v3
	v_pk_add_f32 v[2:3], v[130:131], v[128:129]
	v_fmac_f32_e32 v126, 0xb9800000, v132
	v_mul_f32_e32 v128, v126, v126
	v_mul_f32_e32 v129, v127, v127
	v_pk_add_f32 v[0:1], v[0:1], v[0:1] op_sel:[0,1] op_sel_hi:[1,0]
	v_pk_add_f32 v[2:3], v[2:3], v[2:3] op_sel:[0,1] op_sel_hi:[1,0]
	v_fmamk_f32 v123, v132, 0xb9800000, v123
	v_fmamk_f32 v121, v132, 0xb9800000, v121
	v_mov_b32_e32 v1, v128
	v_mov_b32_e32 v3, v129
	v_fmac_f32_e32 v122, 0xb9800000, v132
	v_fmac_f32_e32 v120, 0xb9800000, v132
	v_fmamk_f32 v125, v132, 0xb9800000, v125
	v_fmac_f32_e32 v124, 0xb9800000, v132
	v_pk_add_f32 v[0:1], v[0:1], v[2:3]
	v_mul_f32_e32 v2, v123, v123
	v_mul_f32_e32 v128, v121, v121
	v_mul_f32_e32 v130, v124, v124
	v_mul_f32_e32 v131, v125, v125
	v_pk_fma_f32 v[2:3], v[122:123], v[122:123], v[2:3] op_sel_hi:[1,1,0]
	v_pk_fma_f32 v[128:129], v[120:121], v[120:121], v[128:129] op_sel_hi:[1,1,0]
	v_mov_b32_e32 v3, v130
	v_mov_b32_e32 v129, v131
	v_pk_add_f32 v[2:3], v[2:3], v[128:129]
	s_nop 0
	v_pk_add_f32 v[0:1], v[0:1], v[2:3]
	s_nop 0
	v_add_f32_e32 v0, v0, v1
	ds_bpermute_b32 v1, v136, v0
	s_waitcnt lgkmcnt(0)
	v_add_f32_e32 v0, v0, v1
	ds_bpermute_b32 v1, v137, v0
	s_waitcnt lgkmcnt(0)
	v_add_f32_e32 v0, v0, v1
	ds_bpermute_b32 v1, v138, v0
	s_waitcnt lgkmcnt(0)
	v_add_f32_e32 v0, v0, v1
	ds_bpermute_b32 v1, v139, v0
	s_waitcnt lgkmcnt(0)
	v_add_f32_e32 v0, v0, v1
	ds_bpermute_b32 v1, v140, v0
	s_waitcnt lgkmcnt(0)
	v_add_f32_e32 v0, v0, v1
	ds_bpermute_b32 v1, v141, v0
	s_waitcnt lgkmcnt(0)
	v_add_f32_e32 v0, v0, v1
	v_mov_b32_e32 v1, 0x3727c5ac
	v_fmamk_f32 v0, v0, 0x39800000, v1
	v_cmp_gt_f32_e32 vcc, s55, v0
	v_mul_f32_e32 v1, 0x4f800000, v0
	s_nop 0
	v_cndmask_b32_e32 v0, v0, v1, vcc
	v_sqrt_f32_e32 v1, v0
	s_nop 0
	v_add_u32_e32 v2, -1, v1
	v_fma_f32 v3, -v2, v1, v0
	v_cmp_ge_f32_e64 s[42:43], 0, v3
	v_add_u32_e32 v3, 1, v1
	s_nop 0
	v_cndmask_b32_e64 v2, v1, v2, s[42:43]
	v_fma_f32 v1, -v3, v1, v0
	v_cmp_lt_f32_e64 s[42:43], 0, v1
	s_nop 1
	v_cndmask_b32_e64 v1, v2, v3, s[42:43]
	v_mul_f32_e32 v2, 0x37800000, v1
	v_cndmask_b32_e32 v1, v1, v2, vcc
	v_cmp_class_f32_e32 vcc, v0, v216
	s_nop 1
	v_cndmask_b32_e32 v0, v1, v0, vcc
	v_div_scale_f32 v1, s[6:7], v0, v0, 1.0
	v_rcp_f32_e32 v2, v1
	s_nop 0
	v_fma_f32 v3, -v1, v2, 1.0
	v_fmac_f32_e32 v2, v3, v2
	v_div_scale_f32 v3, vcc, 1.0, v0, 1.0
	v_mul_f32_e32 v128, v3, v2
	v_fma_f32 v129, -v1, v128, v3
	v_fmac_f32_e32 v128, v129, v2
	v_fma_f32 v1, -v1, v128, v3
	v_div_fmas_f32 v1, v1, v2, v128
	v_div_fixup_f32 v128, v1, v0, 1.0
	global_load_dwordx4 v[142:145], v[8:9], off
	global_load_dwordx4 v[146:149], v[10:11], off
	global_load_dwordx4 v[150:153], v[8:9], off offset:1024
	global_load_dwordx4 v[154:157], v[10:11], off offset:1024
	global_load_dwordx4 v[158:161], v[8:9], off offset:2048
	global_load_dwordx4 v[162:165], v[10:11], off offset:2048
	global_load_dwordx4 v[166:169], v[8:9], off offset:3072
	global_load_dwordx4 v[170:173], v[10:11], off offset:3072
	global_load_dwordx4 v[174:177], v[12:13], off
	global_load_dwordx4 v[178:181], v[14:15], off
	global_load_dwordx4 v[182:185], v[16:17], off
	global_load_dwordx4 v[186:189], v[18:19], off
	global_load_dwordx4 v[194:197], v[20:21], off
	global_load_dwordx4 v[198:201], v[22:23], off
	global_load_dwordx4 v[202:205], v[24:25], off
	global_load_dwordx4 v[206:209], v[26:27], off
	v_pk_mul_f32 v[6:7], v[128:129], v[6:7] op_sel_hi:[0,1]
	v_pk_mul_f32 v[4:5], v[128:129], v[4:5] op_sel_hi:[0,1]
	s_waitcnt vmcnt(14)
	v_pk_fma_f32 v[130:131], v[144:145], v[4:5], v[148:149]
	v_pk_fma_f32 v[132:133], v[142:143], v[6:7], v[146:147]
	v_max_f32_e64 v1, |v130|, |v131|
	v_max_f32_e64 v0, |v132|, |v133|
	v_max3_f32 v129, v0, 0, v1
	s_nop 1
	v_pk_mul_f32 v[74:75], v[128:129], v[74:75] op_sel_hi:[0,1]
	v_pk_mul_f32 v[72:73], v[128:129], v[72:73] op_sel_hi:[0,1]
	s_waitcnt vmcnt(12)
	v_pk_fma_f32 v[72:73], v[152:153], v[72:73], v[156:157]
	v_pk_fma_f32 v[74:75], v[150:151], v[74:75], v[154:155]
	v_max_f32_e64 v1, |v72|, |v73|
	v_max_f32_e64 v0, |v74|, |v75|
	v_max3_f32 v129, v129, v0, v1
	s_nop 1
	v_pk_mul_f32 v[82:83], v[128:129], v[82:83] op_sel_hi:[0,1]
	v_pk_mul_f32 v[78:79], v[128:129], v[78:79] op_sel_hi:[0,1]
	s_waitcnt vmcnt(10)
	v_pk_fma_f32 v[78:79], v[160:161], v[78:79], v[164:165]
	v_pk_fma_f32 v[82:83], v[158:159], v[82:83], v[162:163]
	v_max_f32_e64 v1, |v78|, |v79|
	v_max_f32_e64 v0, |v82|, |v83|
	v_max3_f32 v129, v129, v0, v1
	s_nop 1
	v_pk_mul_f32 v[80:81], v[128:129], v[80:81] op_sel_hi:[0,1]
	v_pk_mul_f32 v[76:77], v[128:129], v[76:77] op_sel_hi:[0,1]
	s_waitcnt vmcnt(8)
	v_pk_fma_f32 v[76:77], v[168:169], v[76:77], v[172:173]
	v_pk_fma_f32 v[80:81], v[166:167], v[80:81], v[170:171]
	v_max_f32_e64 v1, |v76|, |v77|
	v_max_f32_e64 v0, |v80|, |v81|
	v_max3_f32 v129, v129, v0, v1
	s_nop 1
	v_pk_mul_f32 v[90:91], v[128:129], v[90:91] op_sel_hi:[0,1]
	v_pk_mul_f32 v[88:89], v[128:129], v[88:89] op_sel_hi:[0,1]
	s_waitcnt vmcnt(6)
; __global__ void __launch_bounds__(NWAVES * 64, 2) mega_fwd(Args args) {
;     ...
;             for (int j = 0; j < 16; ++j) { const f32x4 gg = *(const f32x4*)(ln1_g + 4 * lane + 256 * j), bb = *(const f32x4*)(ln1_b + 4 * lane + 256 * j);
;                 const f32x4 y = v[j] * rstd * gg + bb; v[j] = y; am = fmaxf(fmaxf(am, fmaxf(fabsf(y[0]), fabsf(y[1]))), fmaxf(fabsf(y[2]), fabsf(y[3]))); }
;             am = fmaxf(wave_max(am, lane), 1e-30f);
;             const float qs = 127.f / am;
;             if (lane == 0) SAq[row] = am * (1.0f / (127.f * 127.f));
	v_pk_fma_f32 v[88:89], v[176:177], v[88:89], v[180:181]
	v_pk_fma_f32 v[90:91], v[174:175], v[90:91], v[178:179]
	v_max_f32_e64 v1, |v88|, |v89|
	v_max_f32_e64 v0, |v90|, |v91|
	v_max3_f32 v129, v129, v0, v1
	s_nop 1
	v_pk_mul_f32 v[94:95], v[128:129], v[94:95] op_sel_hi:[0,1]
	v_pk_mul_f32 v[92:93], v[128:129], v[92:93] op_sel_hi:[0,1]
	s_waitcnt vmcnt(4)
	v_pk_fma_f32 v[92:93], v[184:185], v[92:93], v[188:189]
	v_pk_fma_f32 v[94:95], v[182:183], v[94:95], v[186:187]
	v_max_f32_e64 v1, |v92|, |v93|
	v_max_f32_e64 v0, |v94|, |v95|
	v_max3_f32 v129, v129, v0, v1
	s_nop 1
	v_pk_mul_f32 v[86:87], v[128:129], v[86:87] op_sel_hi:[0,1]
	v_pk_mul_f32 v[84:85], v[128:129], v[84:85] op_sel_hi:[0,1]
	s_waitcnt vmcnt(2)
	v_pk_fma_f32 v[84:85], v[196:197], v[84:85], v[200:201]
	v_pk_fma_f32 v[86:87], v[194:195], v[86:87], v[198:199]
	v_max_f32_e64 v1, |v84|, |v85|
	v_max_f32_e64 v0, |v86|, |v87|
	v_max3_f32 v129, v129, v0, v1
	s_nop 1
	v_pk_mul_f32 v[70:71], v[128:129], v[70:71] op_sel_hi:[0,1]
	v_pk_mul_f32 v[68:69], v[128:129], v[68:69] op_sel_hi:[0,1]
	s_waitcnt vmcnt(0)
	v_pk_fma_f32 v[68:69], v[204:205], v[68:69], v[208:209]
	v_pk_fma_f32 v[70:71], v[202:203], v[70:71], v[206:207]
	v_max_f32_e64 v1, |v68|, |v69|
	v_max_f32_e64 v0, |v70|, |v71|
	v_max3_f32 v129, v129, v0, v1
	global_load_dwordx4 v[142:145], v[28:29], off
	global_load_dwordx4 v[146:149], v[30:31], off
	global_load_dwordx4 v[150:153], v[32:33], off
	global_load_dwordx4 v[154:157], v[34:35], off
	global_load_dwordx4 v[158:161], v[36:37], off
	global_load_dwordx4 v[162:165], v[38:39], off
	global_load_dwordx4 v[166:169], v[40:41], off
	global_load_dwordx4 v[170:173], v[42:43], off
	global_load_dwordx4 v[174:177], v[44:45], off
	global_load_dwordx4 v[178:181], v[46:47], off
	global_load_dwordx4 v[182:185], v[48:49], off
	global_load_dwordx4 v[186:189], v[50:51], off
	global_load_dwordx4 v[194:197], v[52:53], off
	global_load_dwordx4 v[198:201], v[54:55], off
	global_load_dwordx4 v[202:205], v[56:57], off
	global_load_dwordx4 v[206:209], v[58:59], off
	v_pk_mul_f32 v[98:99], v[128:129], v[98:99] op_sel_hi:[0,1]
	v_pk_mul_f32 v[96:97], v[128:129], v[96:97] op_sel_hi:[0,1]
	s_waitcnt vmcnt(14)
	v_pk_fma_f32 v[96:97], v[144:145], v[96:97], v[148:149]
	v_pk_fma_f32 v[98:99], v[142:143], v[98:99], v[146:147]
	v_max_f32_e64 v1, |v96|, |v97|
	v_max_f32_e64 v0, |v98|, |v99|
	v_max3_f32 v129, v129, v0, v1
	s_nop 1
	v_pk_mul_f32 v[102:103], v[128:129], v[102:103] op_sel_hi:[0,1]
	v_pk_mul_f32 v[100:101], v[128:129], v[100:101] op_sel_hi:[0,1]
	s_waitcnt vmcnt(12)
	v_pk_fma_f32 v[100:101], v[152:153], v[100:101], v[156:157]
	v_pk_fma_f32 v[102:103], v[150:151], v[102:103], v[154:155]
	v_max_f32_e64 v1, |v100|, |v101|
	v_max_f32_e64 v0, |v102|, |v103|
	v_max3_f32 v129, v129, v0, v1
	s_nop 1
	v_pk_mul_f32 v[106:107], v[128:129], v[106:107] op_sel_hi:[0,1]
	v_pk_mul_f32 v[104:105], v[128:129], v[104:105] op_sel_hi:[0,1]
	s_waitcnt vmcnt(10)
	v_pk_fma_f32 v[104:105], v[160:161], v[104:105], v[164:165]
	v_pk_fma_f32 v[106:107], v[158:159], v[106:107], v[162:163]
	v_max_f32_e64 v1, |v104|, |v105|
	v_max_f32_e64 v0, |v106|, |v107|
	v_max3_f32 v129, v129, v0, v1
	s_nop 1
	v_pk_mul_f32 v[110:111], v[128:129], v[110:111] op_sel_hi:[0,1]
	v_pk_mul_f32 v[108:109], v[128:129], v[108:109] op_sel_hi:[0,1]
	s_waitcnt vmcnt(8)
	v_pk_fma_f32 v[108:109], v[168:169], v[108:109], v[172:173]
	v_pk_fma_f32 v[110:111], v[166:167], v[110:111], v[170:171]
	v_max_f32_e64 v1, |v108|, |v109|
	v_max_f32_e64 v0, |v110|, |v111|
	v_max3_f32 v129, v129, v0, v1
	s_nop 1
	v_pk_mul_f32 v[114:115], v[128:129], v[114:115] op_sel_hi:[0,1]
	v_pk_mul_f32 v[112:113], v[128:129], v[112:113] op_sel_hi:[0,1]
	s_waitcnt vmcnt(6)
	v_pk_fma_f32 v[112:113], v[176:177], v[112:113], v[180:181]
	v_pk_fma_f32 v[114:115], v[174:175], v[114:115], v[178:179]
	v_max_f32_e64 v1, |v112|, |v113|
	v_max_f32_e64 v0, |v114|, |v115|
	v_max3_f32 v129, v129, v0, v1
	s_nop 1
	v_pk_mul_f32 v[118:119], v[128:129], v[118:119] op_sel_hi:[0,1]
	v_pk_mul_f32 v[116:117], v[128:129], v[116:117] op_sel_hi:[0,1]
	s_waitcnt vmcnt(4)
	v_pk_fma_f32 v[116:117], v[184:185], v[116:117], v[188:189]
	v_pk_fma_f32 v[118:119], v[182:183], v[118:119], v[186:187]
	v_max_f32_e64 v1, |v116|, |v117|
	v_max_f32_e64 v0, |v118|, |v119|
	v_max3_f32 v129, v129, v0, v1
	s_nop 1
	v_pk_mul_f32 v[122:123], v[128:129], v[122:123] op_sel_hi:[0,1]
	v_pk_mul_f32 v[120:121], v[128:129], v[120:121] op_sel_hi:[0,1]
	s_waitcnt vmcnt(2)
	v_pk_fma_f32 v[120:121], v[196:197], v[120:121], v[200:201]
	v_pk_fma_f32 v[122:123], v[194:195], v[122:123], v[198:199]
	v_max_f32_e64 v1, |v120|, |v121|
	v_max_f32_e64 v0, |v122|, |v123|
	v_max3_f32 v129, v129, v0, v1
	s_nop 1
	v_pk_mul_f32 v[126:127], v[128:129], v[126:127] op_sel_hi:[0,1]
	v_pk_mul_f32 v[124:125], v[128:129], v[124:125] op_sel_hi:[0,1]
	s_waitcnt vmcnt(0)
	v_pk_fma_f32 v[2:3], v[204:205], v[124:125], v[208:209]
	v_pk_fma_f32 v[0:1], v[202:203], v[126:127], v[206:207]
	v_max_f32_e64 v5, |v2|, |v3|
	v_max_f32_e64 v4, |v0|, |v1|
	v_max3_f32 v4, v129, v4, v5
	ds_bpermute_b32 v5, v136, v4
	s_waitcnt lgkmcnt(0)
	v_max_f32_e32 v5, v5, v5
	v_max_f32_e32 v4, v4, v5
	ds_bpermute_b32 v5, v137, v4
	s_waitcnt lgkmcnt(0)
	v_max_f32_e32 v5, v5, v5
	v_max_f32_e32 v4, v4, v5
	ds_bpermute_b32 v5, v138, v4
	s_waitcnt lgkmcnt(0)
	v_max_f32_e32 v5, v5, v5
	v_max_f32_e32 v4, v4, v5
	ds_bpermute_b32 v5, v139, v4
	s_waitcnt lgkmcnt(0)
	v_max_f32_e32 v5, v5, v5
	v_max_f32_e32 v4, v4, v5
	ds_bpermute_b32 v5, v140, v4
	s_waitcnt lgkmcnt(0)
	v_max_f32_e32 v5, v5, v5
	v_max_f32_e32 v4, v4, v5
	ds_bpermute_b32 v5, v141, v4
	s_waitcnt lgkmcnt(0)
	v_max3_f32 v4, v4, v5, s5
	s_and_saveexec_b64 s[24:25], s[40:41]
	s_cbranch_execz .LBB0_505
	s_add_u32 s6, s78, s0
	s_addc_u32 s7, s79, s4
	v_mul_f32_e32 v5, 0x38820610, v4
	global_store_dword v193, v5, s[6:7]
	s_branch .LBB0_505

; __device__ __forceinline__ float bflo(unsigned w) { return __uint_as_float(w << 16); }
; __device__ __forceinline__ float bfhi(unsigned w) { return __uint_as_float(w & 0xffff0000u); }
; __global__ void __launch_bounds__(NWAVES * 64, 2) mega_fwd(Args args) {
;     ...
;         for (int row = gw; row < TOK; row += NGW) {
;             const bf16* xr = XB + (size_t)row * DM; const bf16* mr = MP + (size_t)row * DM; float* yr = outg + (size_t)row * DM; f32x4 v[16]; float s = 0.f;
; #pragma unroll
;             for (int j = 0; j < 16; ++j) { const v2u xv = *(const v2u*)(xr + 4 * lane + 256 * j); const v2u m = *(const v2u*)(mr + 4 * lane + 256 * j);
;                 v[j] = (f32x4){bflo(xv[0]), bfhi(xv[0]), bflo(xv[1]), bfhi(xv[1])} * DEEP_ALPHA + (f32x4){bflo(m[0]), bfhi(m[0]), bflo(m[1]), bfhi(m[1])}; s += (v[j][0] + v[j][1]) + (v[j][2] + v[j][3]); }
.LBB0_662:
	v_add_co_u32_e32 v82, vcc, 0xdffff000, v52
	s_brev_b32 s0, 7
	s_nop 0
	v_addc_co_u32_e32 v83, vcc, -1, v53, vcc
	v_add_co_u32_e32 v70, vcc, 0xfffff000, v52
	global_load_dwordx2 v[138:139], v[82:83], off offset:-3584
	s_nop 0
	v_addc_co_u32_e32 v71, vcc, -1, v53, vcc
	global_load_dwordx2 v[140:141], v[70:71], off offset:-3584
	v_add_co_u32_e32 v114, vcc, s0, v52
	s_nop 1
	v_addc_co_u32_e32 v115, vcc, -1, v53, vcc
	s_nop 0
	global_load_dwordx2 v[142:143], v[82:83], off offset:-3072
	global_load_dwordx2 v[144:145], v[70:71], off offset:-3072
	s_nop 0
	global_load_dwordx2 v[146:147], v[82:83], off offset:-2560
	global_load_dwordx2 v[148:149], v[70:71], off offset:-2560
	global_load_dwordx2 v[150:151], v[82:83], off offset:-2048
	global_load_dwordx2 v[152:153], v[70:71], off offset:-2048
	s_nop 0
	s_nop 0
	global_load_dwordx2 v[154:155], v[82:83], off offset:-1536
	global_load_dwordx2 v[156:157], v[70:71], off offset:-1536
	s_nop 0
	global_load_dwordx2 v[158:159], v[82:83], off offset:-1024
	global_load_dwordx2 v[160:161], v[70:71], off offset:-1024
	global_load_dwordx2 v[162:163], v[82:83], off offset:-512
	s_nop 0
	global_load_dwordx2 v[164:165], v[70:71], off offset:-512
	s_nop 0
	s_nop 0
	global_load_dwordx2 v[166:167], v[82:83], off
	s_nop 0
	global_load_dwordx2 v[168:169], v[52:53], off offset:-4096
	s_nop 0
	global_load_dwordx2 v[170:171], v[114:115], off offset:-3584
	global_load_dwordx2 v[172:173], v[52:53], off offset:-3584
	global_load_dwordx2 v[174:175], v[114:115], off offset:-3072
	global_load_dwordx2 v[176:177], v[52:53], off offset:-3072
	s_nop 0
	s_nop 0
	global_load_dwordx2 v[178:179], v[114:115], off offset:-2560
	global_load_dwordx2 v[180:181], v[52:53], off offset:-2560
	s_nop 0
	global_load_dwordx2 v[182:183], v[114:115], off offset:-2048
	global_load_dwordx2 v[184:185], v[52:53], off offset:-2048
	global_load_dwordx2 v[186:187], v[114:115], off offset:-1536
	global_load_dwordx2 v[188:189], v[52:53], off offset:-1536
	s_nop 0
	s_nop 0
	global_load_dwordx2 v[190:191], v[114:115], off offset:-1024
	global_load_dwordx2 v[194:195], v[52:53], off offset:-1024
	s_nop 0
	global_load_dwordx2 v[196:197], v[114:115], off offset:-512
	global_load_dwordx2 v[198:199], v[52:53], off offset:-512
	global_load_dwordx2 v[200:201], v[114:115], off
	s_nop 0
	global_load_dwordx2 v[202:203], v[52:53], off
	s_movk_i32 s0, 0x1000
	s_nop 1
	s_waitcnt vmcnt(31)
	v_lshlrev_b32_e32 v58, 16, v138
	v_and_b32_e32 v59, 0xffff0000, v138
	v_lshlrev_b32_e32 v54, 16, v139
	v_and_b32_e32 v55, 0xffff0000, v139
	s_waitcnt vmcnt(30)
	v_lshlrev_b32_e32 v60, 16, v140
	v_and_b32_e32 v61, 0xffff0000, v140
	v_lshlrev_b32_e32 v56, 16, v141
	v_and_b32_e32 v57, 0xffff0000, v141
	v_pk_fma_f32 v[54:55], v[54:55], s[88:89], v[56:57] op_sel_hi:[1,0,1]
	v_pk_fma_f32 v[56:57], v[58:59], s[88:89], v[60:61] op_sel_hi:[1,0,1]
	v_mov_b32_e32 v61, v55
	v_pk_mov_b32 v[58:59], v[56:57], v[54:55] op_sel:[1,0]
	v_mov_b32_e32 v60, v56
	v_pk_add_f32 v[58:59], v[58:59], v[60:61]
	s_nop 0
	v_add_f32_e32 v58, v58, v59
	v_add_f32_e32 v72, 0, v58
	s_nop 1
	s_waitcnt vmcnt(29)
	v_lshlrev_b32_e32 v62, 16, v142
	v_and_b32_e32 v63, 0xffff0000, v142
	v_lshlrev_b32_e32 v58, 16, v143
	v_and_b32_e32 v59, 0xffff0000, v143
	s_waitcnt vmcnt(28)
	v_lshlrev_b32_e32 v64, 16, v144
	v_and_b32_e32 v65, 0xffff0000, v144
	v_lshlrev_b32_e32 v60, 16, v145
	v_and_b32_e32 v61, 0xffff0000, v145
	v_pk_fma_f32 v[60:61], v[58:59], s[88:89], v[60:61] op_sel_hi:[1,0,1]
	v_pk_fma_f32 v[58:59], v[62:63], s[88:89], v[64:65] op_sel_hi:[1,0,1]
	v_mov_b32_e32 v65, v61
	v_pk_mov_b32 v[62:63], v[58:59], v[60:61] op_sel:[1,0]
	v_mov_b32_e32 v64, v58
	v_pk_add_f32 v[62:63], v[62:63], v[64:65]
	s_nop 0
	v_pk_add_f32 v[74:75], v[62:63], v[62:63] op_sel:[0,1] op_sel_hi:[1,0]
	s_nop 1
	s_waitcnt vmcnt(27)
	v_lshlrev_b32_e32 v66, 16, v146
	v_and_b32_e32 v67, 0xffff0000, v146
	v_lshlrev_b32_e32 v62, 16, v147
	v_and_b32_e32 v63, 0xffff0000, v147
	s_waitcnt vmcnt(26)
	v_lshlrev_b32_e32 v68, 16, v148
	v_and_b32_e32 v69, 0xffff0000, v148
	v_lshlrev_b32_e32 v64, 16, v149
	v_and_b32_e32 v65, 0xffff0000, v149
	v_pk_fma_f32 v[64:65], v[62:63], s[88:89], v[64:65] op_sel_hi:[1,0,1]
	v_pk_fma_f32 v[62:63], v[66:67], s[88:89], v[68:69] op_sel_hi:[1,0,1]
	s_nop 1
	v_add_f32_e32 v76, v62, v63
	v_add_f32_e32 v78, v64, v65
	s_waitcnt vmcnt(25)
	v_lshlrev_b32_e32 v80, 16, v150
	v_and_b32_e32 v81, 0xffff0000, v150
	v_lshlrev_b32_e32 v66, 16, v151
	v_and_b32_e32 v67, 0xffff0000, v151
	s_waitcnt vmcnt(24)
	v_lshlrev_b32_e32 v84, 16, v152
	v_and_b32_e32 v85, 0xffff0000, v152
	v_lshlrev_b32_e32 v68, 16, v153
	v_and_b32_e32 v69, 0xffff0000, v153
	v_pk_fma_f32 v[68:69], v[66:67], s[88:89], v[68:69] op_sel_hi:[1,0,1]
	v_pk_fma_f32 v[66:67], v[80:81], s[88:89], v[84:85] op_sel_hi:[1,0,1]
	v_mov_b32_e32 v77, v68
	v_mov_b32_e32 v73, v66
	v_mov_b32_e32 v75, v67
	v_mov_b32_e32 v79, v69
	v_pk_add_f32 v[72:73], v[72:73], v[74:75]
	v_pk_add_f32 v[74:75], v[76:77], v[78:79]
	s_nop 0
	v_pk_add_f32 v[72:73], v[72:73], v[74:75]
	s_nop 0
	v_pk_add_f32 v[84:85], v[72:73], v[72:73] op_sel:[0,1] op_sel_hi:[1,0]
	s_nop 1
	s_waitcnt vmcnt(23)
	v_lshlrev_b32_e32 v76, 16, v154
	v_and_b32_e32 v77, 0xffff0000, v154
	v_lshlrev_b32_e32 v72, 16, v155
	v_and_b32_e32 v73, 0xffff0000, v155
	s_waitcnt vmcnt(22)
	v_lshlrev_b32_e32 v78, 16, v156
	v_and_b32_e32 v79, 0xffff0000, v156
	v_lshlrev_b32_e32 v74, 16, v157
	v_and_b32_e32 v75, 0xffff0000, v157
	v_pk_fma_f32 v[80:81], v[72:73], s[88:89], v[74:75] op_sel_hi:[1,0,1]
	v_pk_fma_f32 v[78:79], v[76:77], s[88:89], v[78:79] op_sel_hi:[1,0,1]
	v_mov_b32_e32 v75, v81
	v_pk_mov_b32 v[72:73], v[78:79], v[80:81] op_sel:[1,0]
	v_mov_b32_e32 v74, v78
	v_pk_add_f32 v[72:73], v[72:73], v[74:75]
	s_nop 0
	v_pk_add_f32 v[86:87], v[72:73], v[72:73] op_sel:[0,1] op_sel_hi:[1,0]
	s_nop 1
	s_waitcnt vmcnt(21)
; __device__ __forceinline__ float bflo(unsigned w) { return __uint_as_float(w << 16); }
; __device__ __forceinline__ float bfhi(unsigned w) { return __uint_as_float(w & 0xffff0000u); }
; __global__ void __launch_bounds__(NWAVES * 64, 2) mega_fwd(Args args) {
;     ...
;             for (int j = 0; j < 16; ++j) { const v2u xv = *(const v2u*)(xr + 4 * lane + 256 * j); const v2u m = *(const v2u*)(mr + 4 * lane + 256 * j);
;                 v[j] = (f32x4){bflo(xv[0]), bfhi(xv[0]), bflo(xv[1]), bfhi(xv[1])} * DEEP_ALPHA + (f32x4){bflo(m[0]), bfhi(m[0]), bflo(m[1]), bfhi(m[1])}; s += (v[j][0] + v[j][1]) + (v[j][2] + v[j][3]); }
	v_lshlrev_b32_e32 v88, 16, v158
	v_and_b32_e32 v89, 0xffff0000, v158
	v_lshlrev_b32_e32 v72, 16, v159
	v_and_b32_e32 v73, 0xffff0000, v159
	s_waitcnt vmcnt(20)
	v_lshlrev_b32_e32 v90, 16, v160
	v_and_b32_e32 v91, 0xffff0000, v160
	v_lshlrev_b32_e32 v74, 16, v161
	v_and_b32_e32 v75, 0xffff0000, v161
	v_pk_fma_f32 v[76:77], v[72:73], s[88:89], v[74:75] op_sel_hi:[1,0,1]
	s_nop 1
	v_pk_fma_f32 v[74:75], v[88:89], s[88:89], v[90:91] op_sel_hi:[1,0,1]
	v_add_f32_e32 v90, v76, v77
	v_add_f32_e32 v88, v74, v75
	s_waitcnt vmcnt(19)
	v_lshlrev_b32_e32 v92, 16, v162
	v_and_b32_e32 v93, 0xffff0000, v162
	v_lshlrev_b32_e32 v72, 16, v163
	v_and_b32_e32 v73, 0xffff0000, v163
	s_waitcnt vmcnt(18)
	v_lshlrev_b32_e32 v94, 16, v164
	v_and_b32_e32 v95, 0xffff0000, v164
	v_lshlrev_b32_e32 v70, 16, v165
	v_and_b32_e32 v71, 0xffff0000, v165
	v_pk_fma_f32 v[72:73], v[72:73], s[88:89], v[70:71] op_sel_hi:[1,0,1]
	v_pk_fma_f32 v[70:71], v[92:93], s[88:89], v[94:95] op_sel_hi:[1,0,1]
	v_mov_b32_e32 v89, v72
	v_mov_b32_e32 v85, v70
	v_mov_b32_e32 v87, v71
	v_mov_b32_e32 v91, v73
	v_pk_add_f32 v[84:85], v[84:85], v[86:87]
	v_pk_add_f32 v[86:87], v[88:89], v[90:91]
	s_nop 0
	v_pk_add_f32 v[84:85], v[84:85], v[86:87]
	s_nop 0
	v_pk_add_f32 v[94:95], v[84:85], v[84:85] op_sel:[0,1] op_sel_hi:[1,0]
	s_nop 1
	s_waitcnt vmcnt(17)
	v_lshlrev_b32_e32 v86, 16, v166
	v_and_b32_e32 v87, 0xffff0000, v166
	v_lshlrev_b32_e32 v82, 16, v167
	v_and_b32_e32 v83, 0xffff0000, v167
	s_waitcnt vmcnt(16)
	v_lshlrev_b32_e32 v88, 16, v168
	v_and_b32_e32 v89, 0xffff0000, v168
	v_lshlrev_b32_e32 v84, 16, v169
	v_and_b32_e32 v85, 0xffff0000, v169
	v_pk_fma_f32 v[84:85], v[82:83], s[88:89], v[84:85] op_sel_hi:[1,0,1]
	v_pk_fma_f32 v[82:83], v[86:87], s[88:89], v[88:89] op_sel_hi:[1,0,1]
	v_mov_b32_e32 v89, v85
	v_pk_mov_b32 v[86:87], v[82:83], v[84:85] op_sel:[1,0]
	v_mov_b32_e32 v88, v82
	v_pk_add_f32 v[86:87], v[86:87], v[88:89]
	s_nop 0
	v_pk_add_f32 v[96:97], v[86:87], v[86:87] op_sel:[0,1] op_sel_hi:[1,0]
	s_nop 1
	s_waitcnt vmcnt(15)
	v_lshlrev_b32_e32 v90, 16, v170
	v_and_b32_e32 v91, 0xffff0000, v170
	v_lshlrev_b32_e32 v86, 16, v171
	v_and_b32_e32 v87, 0xffff0000, v171
	s_waitcnt vmcnt(14)
	v_lshlrev_b32_e32 v92, 16, v172
	v_and_b32_e32 v93, 0xffff0000, v172
	v_lshlrev_b32_e32 v88, 16, v173
	v_and_b32_e32 v89, 0xffff0000, v173
	v_pk_fma_f32 v[88:89], v[86:87], s[88:89], v[88:89] op_sel_hi:[1,0,1]
	v_pk_fma_f32 v[86:87], v[90:91], s[88:89], v[92:93] op_sel_hi:[1,0,1]
	s_nop 1
	v_add_f32_e32 v98, v86, v87
	v_add_f32_e32 v100, v88, v89
	s_waitcnt vmcnt(13)
	v_lshlrev_b32_e32 v102, 16, v174
	v_and_b32_e32 v103, 0xffff0000, v174
	v_lshlrev_b32_e32 v90, 16, v175
	v_and_b32_e32 v91, 0xffff0000, v175
	s_waitcnt vmcnt(12)
	v_lshlrev_b32_e32 v104, 16, v176
	v_and_b32_e32 v105, 0xffff0000, v176
	v_lshlrev_b32_e32 v92, 16, v177
	v_and_b32_e32 v93, 0xffff0000, v177
	v_pk_fma_f32 v[92:93], v[90:91], s[88:89], v[92:93] op_sel_hi:[1,0,1]
	v_pk_fma_f32 v[90:91], v[102:103], s[88:89], v[104:105] op_sel_hi:[1,0,1]
	v_mov_b32_e32 v99, v92
	v_mov_b32_e32 v95, v90
	v_mov_b32_e32 v97, v91
	v_mov_b32_e32 v101, v93
	v_pk_add_f32 v[94:95], v[94:95], v[96:97]
	v_pk_add_f32 v[96:97], v[98:99], v[100:101]
	s_nop 0
	v_pk_add_f32 v[94:95], v[94:95], v[96:97]
	s_nop 0
	v_pk_add_f32 v[106:107], v[94:95], v[94:95] op_sel:[0,1] op_sel_hi:[1,0]
	s_nop 1
	s_waitcnt vmcnt(11)
	v_lshlrev_b32_e32 v98, 16, v178
	v_and_b32_e32 v99, 0xffff0000, v178
	v_lshlrev_b32_e32 v94, 16, v179
	v_and_b32_e32 v95, 0xffff0000, v179
	s_waitcnt vmcnt(10)
	v_lshlrev_b32_e32 v100, 16, v180
	v_and_b32_e32 v101, 0xffff0000, v180
	v_lshlrev_b32_e32 v96, 16, v181
	v_and_b32_e32 v97, 0xffff0000, v181
	v_pk_fma_f32 v[96:97], v[94:95], s[88:89], v[96:97] op_sel_hi:[1,0,1]
	v_pk_fma_f32 v[94:95], v[98:99], s[88:89], v[100:101] op_sel_hi:[1,0,1]
	v_mov_b32_e32 v101, v97
	v_pk_mov_b32 v[98:99], v[94:95], v[96:97] op_sel:[1,0]
	v_mov_b32_e32 v100, v94
	v_pk_add_f32 v[98:99], v[98:99], v[100:101]
	s_nop 0
	v_pk_add_f32 v[108:109], v[98:99], v[98:99] op_sel:[0,1] op_sel_hi:[1,0]
	s_nop 1
	s_waitcnt vmcnt(9)
	v_lshlrev_b32_e32 v102, 16, v182
	v_and_b32_e32 v103, 0xffff0000, v182
	v_lshlrev_b32_e32 v98, 16, v183
	v_and_b32_e32 v99, 0xffff0000, v183
	s_waitcnt vmcnt(8)
	v_lshlrev_b32_e32 v104, 16, v184
	v_and_b32_e32 v105, 0xffff0000, v184
	v_lshlrev_b32_e32 v100, 16, v185
	v_and_b32_e32 v101, 0xffff0000, v185
	v_pk_fma_f32 v[100:101], v[98:99], s[88:89], v[100:101] op_sel_hi:[1,0,1]
	v_pk_fma_f32 v[98:99], v[102:103], s[88:89], v[104:105] op_sel_hi:[1,0,1]
	s_nop 1
	v_add_f32_e32 v110, v98, v99
	v_add_f32_e32 v112, v100, v101
	s_waitcnt vmcnt(7)
	v_lshlrev_b32_e32 v116, 16, v186
	v_and_b32_e32 v117, 0xffff0000, v186
	v_lshlrev_b32_e32 v102, 16, v187
	v_and_b32_e32 v103, 0xffff0000, v187
	s_waitcnt vmcnt(6)
	v_lshlrev_b32_e32 v118, 16, v188
	v_and_b32_e32 v119, 0xffff0000, v188
	v_lshlrev_b32_e32 v104, 16, v189
	v_and_b32_e32 v105, 0xffff0000, v189
	v_pk_fma_f32 v[104:105], v[102:103], s[88:89], v[104:105] op_sel_hi:[1,0,1]
	v_pk_fma_f32 v[102:103], v[116:117], s[88:89], v[118:119] op_sel_hi:[1,0,1]
	v_mov_b32_e32 v111, v104
	v_mov_b32_e32 v107, v102
	v_mov_b32_e32 v109, v103
	v_mov_b32_e32 v113, v105
	v_pk_add_f32 v[106:107], v[106:107], v[108:109]
	v_pk_add_f32 v[108:109], v[110:111], v[112:113]
	s_nop 0
	v_pk_add_f32 v[106:107], v[106:107], v[108:109]
	s_nop 0
	v_pk_add_f32 v[118:119], v[106:107], v[106:107] op_sel:[0,1] op_sel_hi:[1,0]
	s_nop 1
	s_waitcnt vmcnt(5)
	v_lshlrev_b32_e32 v110, 16, v190
	v_and_b32_e32 v111, 0xffff0000, v190
	v_lshlrev_b32_e32 v106, 16, v191
	v_and_b32_e32 v107, 0xffff0000, v191
	s_waitcnt vmcnt(4)
; __device__ __forceinline__ float bflo(unsigned w) { return __uint_as_float(w << 16); }
; __device__ __forceinline__ float bfhi(unsigned w) { return __uint_as_float(w & 0xffff0000u); }
; __global__ void __launch_bounds__(NWAVES * 64, 2) mega_fwd(Args args) {
;     ...
;             for (int j = 0; j < 16; ++j) { const v2u xv = *(const v2u*)(xr + 4 * lane + 256 * j); const v2u m = *(const v2u*)(mr + 4 * lane + 256 * j);
;                 v[j] = (f32x4){bflo(xv[0]), bfhi(xv[0]), bflo(xv[1]), bfhi(xv[1])} * DEEP_ALPHA + (f32x4){bflo(m[0]), bfhi(m[0]), bflo(m[1]), bfhi(m[1])}; s += (v[j][0] + v[j][1]) + (v[j][2] + v[j][3]); }
;             const float mean = wave_sum(s, lane) * (1.0f / DM); float q = 0.f;
; #pragma unroll
;             for (int j = 0; j < 16; ++j) { v[j] = v[j] - mean; q += (v[j][0] * v[j][0] + v[j][1] * v[j][1]) + (v[j][2] * v[j][2] + v[j][3] * v[j][3]); }
	v_lshlrev_b32_e32 v112, 16, v194
	v_and_b32_e32 v113, 0xffff0000, v194
	v_lshlrev_b32_e32 v108, 16, v195
	v_and_b32_e32 v109, 0xffff0000, v195
	v_pk_fma_f32 v[108:109], v[106:107], s[88:89], v[108:109] op_sel_hi:[1,0,1]
	v_pk_fma_f32 v[106:107], v[110:111], s[88:89], v[112:113] op_sel_hi:[1,0,1]
	v_mov_b32_e32 v113, v109
	v_pk_mov_b32 v[110:111], v[106:107], v[108:109] op_sel:[1,0]
	v_mov_b32_e32 v112, v106
	v_pk_add_f32 v[110:111], v[110:111], v[112:113]
	s_nop 0
	v_pk_add_f32 v[120:121], v[110:111], v[110:111] op_sel:[0,1] op_sel_hi:[1,0]
	s_nop 1
	s_waitcnt vmcnt(3)
	v_lshlrev_b32_e32 v116, 16, v196
	v_and_b32_e32 v117, 0xffff0000, v196
	v_lshlrev_b32_e32 v110, 16, v197
	v_and_b32_e32 v111, 0xffff0000, v197
	s_waitcnt vmcnt(2)
	v_lshlrev_b32_e32 v122, 16, v198
	v_and_b32_e32 v123, 0xffff0000, v198
	v_lshlrev_b32_e32 v112, 16, v199
	v_and_b32_e32 v113, 0xffff0000, v199
	v_pk_fma_f32 v[112:113], v[110:111], s[88:89], v[112:113] op_sel_hi:[1,0,1]
	v_pk_fma_f32 v[110:111], v[116:117], s[88:89], v[122:123] op_sel_hi:[1,0,1]
	s_nop 1
	v_add_f32_e32 v122, v110, v111
	v_add_f32_e32 v124, v112, v113
	s_waitcnt vmcnt(1)
	v_lshlrev_b32_e32 v132, 16, v200
	v_and_b32_e32 v133, 0xffff0000, v200
	v_lshlrev_b32_e32 v114, 16, v201
	v_and_b32_e32 v115, 0xffff0000, v201
	s_waitcnt vmcnt(0)
	v_lshlrev_b32_e32 v134, 16, v202
	v_and_b32_e32 v135, 0xffff0000, v202
	v_lshlrev_b32_e32 v116, 16, v203
	v_and_b32_e32 v117, 0xffff0000, v203
	v_pk_fma_f32 v[114:115], v[114:115], s[88:89], v[116:117] op_sel_hi:[1,0,1]
	v_pk_fma_f32 v[116:117], v[132:133], s[88:89], v[134:135] op_sel_hi:[1,0,1]
	v_mov_b32_e32 v123, v114
	v_mov_b32_e32 v119, v116
	v_mov_b32_e32 v121, v117
	v_mov_b32_e32 v125, v115
	v_pk_add_f32 v[118:119], v[118:119], v[120:121]
	v_pk_add_f32 v[120:121], v[122:123], v[124:125]
	s_nop 0
	v_pk_add_f32 v[118:119], v[118:119], v[120:121]
	s_nop 0
	v_add_f32_e32 v118, v118, v119
	ds_bpermute_b32 v119, v126, v118
	s_waitcnt lgkmcnt(0)
	v_add_f32_e32 v118, v118, v119
	ds_bpermute_b32 v119, v127, v118
	s_waitcnt lgkmcnt(0)
	v_add_f32_e32 v118, v118, v119
	ds_bpermute_b32 v119, v128, v118
	s_waitcnt lgkmcnt(0)
	v_add_f32_e32 v118, v118, v119
	ds_bpermute_b32 v119, v129, v118
	s_waitcnt lgkmcnt(0)
	v_add_f32_e32 v118, v118, v119
	ds_bpermute_b32 v119, v130, v118
	s_waitcnt lgkmcnt(0)
	v_add_f32_e32 v118, v118, v119
	ds_bpermute_b32 v119, v131, v118
	s_waitcnt lgkmcnt(0)
	v_add_f32_e32 v132, v118, v119
	v_fmamk_f32 v57, v132, 0xb9800000, v57
	v_fmac_f32_e32 v56, 0xb9800000, v132
	v_fmamk_f32 v55, v132, 0xb9800000, v55
	v_fmac_f32_e32 v54, 0xb9800000, v132
	v_pk_mul_f32 v[118:119], v[54:55], v[54:55]
	v_pk_mul_f32 v[120:121], v[56:57], v[56:57]
	v_fmamk_f32 v59, v132, 0xb9800000, v59
	v_pk_mov_b32 v[122:123], v[120:121], v[118:119] op_sel:[1,0]
	v_mov_b32_e32 v121, v119
	v_fmac_f32_e32 v58, 0xb9800000, v132
	v_fmamk_f32 v61, v132, 0xb9800000, v61
	v_fmac_f32_e32 v60, 0xb9800000, v132
	v_pk_add_f32 v[118:119], v[122:123], v[120:121]
	v_pk_mul_f32 v[120:121], v[60:61], v[60:61]
	v_pk_mul_f32 v[122:123], v[58:59], v[58:59]
	v_fmamk_f32 v67, v132, 0xb9800000, v67
	v_pk_mov_b32 v[124:125], v[122:123], v[120:121] op_sel:[1,0]
	v_mov_b32_e32 v123, v121
	v_pk_add_f32 v[120:121], v[124:125], v[122:123]
	v_fmac_f32_e32 v66, 0xb9800000, v132
	v_mul_f32_e32 v122, v66, v66
	v_mul_f32_e32 v123, v67, v67
	v_pk_add_f32 v[118:119], v[118:119], v[118:119] op_sel:[0,1] op_sel_hi:[1,0]
	v_pk_add_f32 v[120:121], v[120:121], v[120:121] op_sel:[0,1] op_sel_hi:[1,0]
	v_fmamk_f32 v63, v132, 0xb9800000, v63
	v_fmamk_f32 v65, v132, 0xb9800000, v65
	v_mov_b32_e32 v119, v122
	v_mov_b32_e32 v121, v123
	v_fmac_f32_e32 v62, 0xb9800000, v132
	v_fmac_f32_e32 v64, 0xb9800000, v132
	v_fmamk_f32 v69, v132, 0xb9800000, v69
	v_fmac_f32_e32 v68, 0xb9800000, v132
	v_pk_add_f32 v[118:119], v[118:119], v[120:121]
	v_mul_f32_e32 v120, v63, v63
	v_mul_f32_e32 v122, v65, v65
	v_mul_f32_e32 v124, v68, v68
	v_mul_f32_e32 v125, v69, v69
	v_pk_fma_f32 v[120:121], v[62:63], v[62:63], v[120:121] op_sel_hi:[1,1,0]
	v_pk_fma_f32 v[122:123], v[64:65], v[64:65], v[122:123] op_sel_hi:[1,1,0]
	v_mov_b32_e32 v121, v124
	v_mov_b32_e32 v123, v125
	v_pk_add_f32 v[120:121], v[120:121], v[122:123]
	v_fmamk_f32 v79, v132, 0xb9800000, v79
	v_fmac_f32_e32 v78, 0xb9800000, v132
	v_fmamk_f32 v81, v132, 0xb9800000, v81
	v_fmac_f32_e32 v80, 0xb9800000, v132
	v_pk_add_f32 v[118:119], v[118:119], v[120:121]
	v_pk_mul_f32 v[120:121], v[80:81], v[80:81]
	v_pk_mul_f32 v[122:123], v[78:79], v[78:79]
	v_fmamk_f32 v71, v132, 0xb9800000, v71
	v_pk_mov_b32 v[124:125], v[122:123], v[120:121] op_sel:[1,0]
	v_mov_b32_e32 v123, v121
	v_pk_add_f32 v[120:121], v[124:125], v[122:123]
	v_fmac_f32_e32 v70, 0xb9800000, v132
	v_mul_f32_e32 v122, v70, v70
	v_mul_f32_e32 v123, v71, v71
	v_pk_add_f32 v[118:119], v[118:119], v[118:119] op_sel:[0,1] op_sel_hi:[1,0]
	v_pk_add_f32 v[120:121], v[120:121], v[120:121] op_sel:[0,1] op_sel_hi:[1,0]
	v_fmamk_f32 v75, v132, 0xb9800000, v75
	v_fmamk_f32 v77, v132, 0xb9800000, v77
	v_mov_b32_e32 v119, v122
	v_mov_b32_e32 v121, v123
	v_fmac_f32_e32 v74, 0xb9800000, v132
	v_fmac_f32_e32 v76, 0xb9800000, v132
	v_fmamk_f32 v73, v132, 0xb9800000, v73
	v_fmac_f32_e32 v72, 0xb9800000, v132
	v_pk_add_f32 v[118:119], v[118:119], v[120:121]
	v_mul_f32_e32 v120, v75, v75
	v_mul_f32_e32 v122, v77, v77
	v_mul_f32_e32 v124, v72, v72
	v_mul_f32_e32 v125, v73, v73
	v_pk_fma_f32 v[120:121], v[74:75], v[74:75], v[120:121] op_sel_hi:[1,1,0]
	v_pk_fma_f32 v[122:123], v[76:77], v[76:77], v[122:123] op_sel_hi:[1,1,0]
	v_mov_b32_e32 v121, v124
	v_mov_b32_e32 v123, v125
	v_pk_add_f32 v[120:121], v[120:121], v[122:123]
; __global__ void __launch_bounds__(NWAVES * 64, 2) mega_fwd(Args args) {
;     ...
;             const float mean = wave_sum(s, lane) * (1.0f / DM); float q = 0.f;
; #pragma unroll
;             for (int j = 0; j < 16; ++j) { v[j] = v[j] - mean; q += (v[j][0] * v[j][0] + v[j][1] * v[j][1]) + (v[j][2] * v[j][2] + v[j][3] * v[j][3]); }
;             const float rstd = 1.0f / sqrtf(wave_sum(q, lane) * (1.0f / DM) + LN_EPS);
	v_fmamk_f32 v83, v132, 0xb9800000, v83
	v_fmac_f32_e32 v82, 0xb9800000, v132
	v_fmamk_f32 v85, v132, 0xb9800000, v85
	v_fmac_f32_e32 v84, 0xb9800000, v132
	v_pk_add_f32 v[118:119], v[118:119], v[120:121]
	v_pk_mul_f32 v[120:121], v[84:85], v[84:85]
	v_pk_mul_f32 v[122:123], v[82:83], v[82:83]
	v_fmamk_f32 v91, v132, 0xb9800000, v91
	v_pk_mov_b32 v[124:125], v[122:123], v[120:121] op_sel:[1,0]
	v_mov_b32_e32 v123, v121
	v_pk_add_f32 v[120:121], v[124:125], v[122:123]
	v_fmac_f32_e32 v90, 0xb9800000, v132
	v_mul_f32_e32 v122, v90, v90
	v_mul_f32_e32 v123, v91, v91
	v_pk_add_f32 v[118:119], v[118:119], v[118:119] op_sel:[0,1] op_sel_hi:[1,0]
	v_pk_add_f32 v[120:121], v[120:121], v[120:121] op_sel:[0,1] op_sel_hi:[1,0]
	v_fmamk_f32 v87, v132, 0xb9800000, v87
	v_fmamk_f32 v89, v132, 0xb9800000, v89
	v_mov_b32_e32 v119, v122
	v_mov_b32_e32 v121, v123
	v_fmac_f32_e32 v86, 0xb9800000, v132
	v_fmac_f32_e32 v88, 0xb9800000, v132
	v_fmamk_f32 v93, v132, 0xb9800000, v93
	v_fmac_f32_e32 v92, 0xb9800000, v132
	v_pk_add_f32 v[118:119], v[118:119], v[120:121]
	v_mul_f32_e32 v120, v87, v87
	v_mul_f32_e32 v122, v89, v89
	v_mul_f32_e32 v124, v92, v92
	v_mul_f32_e32 v125, v93, v93
	v_pk_fma_f32 v[120:121], v[86:87], v[86:87], v[120:121] op_sel_hi:[1,1,0]
	v_pk_fma_f32 v[122:123], v[88:89], v[88:89], v[122:123] op_sel_hi:[1,1,0]
	v_mov_b32_e32 v121, v124
	v_mov_b32_e32 v123, v125
	v_pk_add_f32 v[120:121], v[120:121], v[122:123]
	v_fmamk_f32 v95, v132, 0xb9800000, v95
	v_fmac_f32_e32 v94, 0xb9800000, v132
	v_fmamk_f32 v97, v132, 0xb9800000, v97
	v_fmac_f32_e32 v96, 0xb9800000, v132
	v_pk_add_f32 v[118:119], v[118:119], v[120:121]
	v_pk_mul_f32 v[120:121], v[96:97], v[96:97]
	v_pk_mul_f32 v[122:123], v[94:95], v[94:95]
	v_fmamk_f32 v103, v132, 0xb9800000, v103
	v_pk_mov_b32 v[124:125], v[122:123], v[120:121] op_sel:[1,0]
	v_mov_b32_e32 v123, v121
	v_pk_add_f32 v[120:121], v[124:125], v[122:123]
	v_fmac_f32_e32 v102, 0xb9800000, v132
	v_mul_f32_e32 v122, v102, v102
	v_mul_f32_e32 v123, v103, v103
	v_pk_add_f32 v[118:119], v[118:119], v[118:119] op_sel:[0,1] op_sel_hi:[1,0]
	v_pk_add_f32 v[120:121], v[120:121], v[120:121] op_sel:[0,1] op_sel_hi:[1,0]
	v_fmamk_f32 v99, v132, 0xb9800000, v99
	v_fmamk_f32 v101, v132, 0xb9800000, v101
	v_mov_b32_e32 v119, v122
	v_mov_b32_e32 v121, v123
	v_fmac_f32_e32 v98, 0xb9800000, v132
	v_fmac_f32_e32 v100, 0xb9800000, v132
	v_fmamk_f32 v105, v132, 0xb9800000, v105
	v_fmac_f32_e32 v104, 0xb9800000, v132
	v_pk_add_f32 v[118:119], v[118:119], v[120:121]
	v_mul_f32_e32 v120, v99, v99
	v_mul_f32_e32 v122, v101, v101
	v_mul_f32_e32 v124, v104, v104
	v_mul_f32_e32 v125, v105, v105
	v_pk_fma_f32 v[120:121], v[98:99], v[98:99], v[120:121] op_sel_hi:[1,1,0]
	v_pk_fma_f32 v[122:123], v[100:101], v[100:101], v[122:123] op_sel_hi:[1,1,0]
	v_mov_b32_e32 v121, v124
	v_mov_b32_e32 v123, v125
	v_pk_add_f32 v[120:121], v[120:121], v[122:123]
	v_fmamk_f32 v107, v132, 0xb9800000, v107
	v_fmac_f32_e32 v106, 0xb9800000, v132
	v_fmamk_f32 v109, v132, 0xb9800000, v109
	v_fmac_f32_e32 v108, 0xb9800000, v132
	v_pk_add_f32 v[118:119], v[118:119], v[120:121]
	v_pk_mul_f32 v[120:121], v[108:109], v[108:109]
	v_pk_mul_f32 v[122:123], v[106:107], v[106:107]
	v_fmamk_f32 v117, v132, 0xb9800000, v117
	v_pk_mov_b32 v[124:125], v[122:123], v[120:121] op_sel:[1,0]
	v_mov_b32_e32 v123, v121
	v_pk_add_f32 v[120:121], v[124:125], v[122:123]
	v_fmac_f32_e32 v116, 0xb9800000, v132
	v_mul_f32_e32 v122, v116, v116
	v_mul_f32_e32 v123, v117, v117
	v_pk_add_f32 v[118:119], v[118:119], v[118:119] op_sel:[0,1] op_sel_hi:[1,0]
	v_pk_add_f32 v[120:121], v[120:121], v[120:121] op_sel:[0,1] op_sel_hi:[1,0]
	v_fmamk_f32 v111, v132, 0xb9800000, v111
	v_fmamk_f32 v113, v132, 0xb9800000, v113
	v_mov_b32_e32 v119, v122
	v_mov_b32_e32 v121, v123
	v_fmac_f32_e32 v110, 0xb9800000, v132
	v_fmac_f32_e32 v112, 0xb9800000, v132
	v_fmamk_f32 v115, v132, 0xb9800000, v115
	v_fmac_f32_e32 v114, 0xb9800000, v132
	v_pk_add_f32 v[118:119], v[118:119], v[120:121]
	v_mul_f32_e32 v120, v111, v111
	v_mul_f32_e32 v122, v113, v113
	v_mul_f32_e32 v124, v114, v114
	v_mul_f32_e32 v125, v115, v115
	v_pk_fma_f32 v[120:121], v[110:111], v[110:111], v[120:121] op_sel_hi:[1,1,0]
	v_pk_fma_f32 v[122:123], v[112:113], v[112:113], v[122:123] op_sel_hi:[1,1,0]
	v_mov_b32_e32 v121, v124
	v_mov_b32_e32 v123, v125
	v_pk_add_f32 v[120:121], v[120:121], v[122:123]
	s_nop 0
	v_pk_add_f32 v[118:119], v[118:119], v[120:121]
	s_nop 0
	v_add_f32_e32 v118, v118, v119
	ds_bpermute_b32 v119, v126, v118
	s_waitcnt lgkmcnt(0)
	v_add_f32_e32 v118, v118, v119
	ds_bpermute_b32 v119, v127, v118
	s_waitcnt lgkmcnt(0)
	v_add_f32_e32 v118, v118, v119
	ds_bpermute_b32 v119, v128, v118
	s_waitcnt lgkmcnt(0)
	v_add_f32_e32 v118, v118, v119
	ds_bpermute_b32 v119, v129, v118
	s_waitcnt lgkmcnt(0)
	v_add_f32_e32 v118, v118, v119
	ds_bpermute_b32 v119, v130, v118
	s_waitcnt lgkmcnt(0)
	v_add_f32_e32 v118, v118, v119
	ds_bpermute_b32 v119, v131, v118
	s_waitcnt lgkmcnt(0)
; __global__ void __launch_bounds__(NWAVES * 64, 2) mega_fwd(Args args) {
;     ...
;             const float rstd = 1.0f / sqrtf(wave_sum(q, lane) * (1.0f / DM) + LN_EPS);
; #pragma unroll
;             for (int j = 0; j < 16; ++j) { const f32x4 gg = *(const f32x4*)(ln2_g + 4 * lane + 256 * j), bb = *(const f32x4*)(ln2_b + 4 * lane + 256 * j);
;                 *(f32x4*)(yr + 4 * lane + 256 * j) = v[j] * rstd * gg + bb; }
	v_add_f32_e32 v118, v118, v119
	v_mov_b32_e32 v119, 0x3727c5ac
	v_fmamk_f32 v118, v118, 0x39800000, v119
	v_cmp_gt_f32_e32 vcc, s55, v118
	v_mul_f32_e32 v119, 0x4f800000, v118
	s_nop 0
	v_cndmask_b32_e32 v118, v118, v119, vcc
	v_sqrt_f32_e32 v119, v118
	s_nop 0
	v_add_u32_e32 v120, -1, v119
	v_fma_f32 v121, -v120, v119, v118
	v_cmp_ge_f32_e64 s[38:39], 0, v121
	v_add_u32_e32 v121, 1, v119
	s_nop 0
	v_cndmask_b32_e64 v120, v119, v120, s[38:39]
	v_fma_f32 v119, -v121, v119, v118
	v_cmp_lt_f32_e64 s[38:39], 0, v119
	s_nop 1
	v_cndmask_b32_e64 v119, v120, v121, s[38:39]
	v_mul_f32_e32 v120, 0x37800000, v119
	v_cndmask_b32_e32 v119, v119, v120, vcc
	v_cmp_class_f32_e32 vcc, v118, v216
	s_nop 1
	v_cndmask_b32_e32 v118, v119, v118, vcc
	v_div_scale_f32 v119, s[4:5], v118, v118, 1.0
	v_rcp_f32_e32 v120, v119
	v_readlane_b32 s4, v255, 30
	v_readlane_b32 s5, v255, 31
	v_fma_f32 v121, -v119, v120, 1.0
	v_fmac_f32_e32 v120, v121, v120
	v_div_scale_f32 v121, vcc, 1.0, v118, 1.0
	v_mul_f32_e32 v122, v121, v120
	v_fma_f32 v123, -v119, v122, v121
	v_fmac_f32_e32 v122, v123, v120
	v_fma_f32 v119, -v119, v122, v121
	v_div_fmas_f32 v119, v119, v120, v122
	global_load_dwordx4 v[122:125], v[0:1], off
	global_load_dwordx4 v[132:135], v[2:3], off
	v_div_fixup_f32 v118, v119, v118, 1.0
	v_pk_mul_f32 v[136:137], v[118:119], v[56:57] op_sel_hi:[0,1]
	v_pk_mul_f32 v[54:55], v[118:119], v[54:55] op_sel_hi:[0,1]
	v_lshl_add_u64 v[120:121], s[42:43], 0, v[192:193]
	v_pk_mul_f32 v[60:61], v[118:119], v[60:61] op_sel_hi:[0,1]
	v_pk_mul_f32 v[58:59], v[118:119], v[58:59] op_sel_hi:[0,1]
	v_pk_mul_f32 v[64:65], v[118:119], v[64:65] op_sel_hi:[0,1]
	v_pk_mul_f32 v[62:63], v[118:119], v[62:63] op_sel_hi:[0,1]
	s_waitcnt vmcnt(0)
	v_pk_fma_f32 v[56:57], v[124:125], v[54:55], v[134:135]
	v_pk_fma_f32 v[54:55], v[122:123], v[136:137], v[132:133]
	global_store_dwordx4 v[120:121], v[54:57], off
	global_load_dwordx4 v[54:57], v[0:1], off offset:1024
	s_nop 0
	global_load_dwordx4 v[122:125], v[2:3], off offset:1024
	s_waitcnt vmcnt(0)
	v_pk_fma_f32 v[54:55], v[54:55], v[58:59], v[122:123]
	v_pk_fma_f32 v[56:57], v[56:57], v[60:61], v[124:125]
	global_store_dwordx4 v[120:121], v[54:57], off offset:1024
	global_load_dwordx4 v[54:57], v[0:1], off offset:2048
	s_nop 0
	global_load_dwordx4 v[58:61], v[2:3], off offset:2048
	s_waitcnt vmcnt(0)
	v_pk_fma_f32 v[54:55], v[54:55], v[62:63], v[58:59]
	v_pk_fma_f32 v[56:57], v[56:57], v[64:65], v[60:61]
	global_store_dwordx4 v[120:121], v[54:57], off offset:2048
	global_load_dwordx4 v[54:57], v[0:1], off offset:3072
	s_nop 0
	global_load_dwordx4 v[58:61], v[2:3], off offset:3072
	v_pk_mul_f32 v[62:63], v[118:119], v[68:69] op_sel_hi:[0,1]
	v_pk_mul_f32 v[64:65], v[118:119], v[66:67] op_sel_hi:[0,1]
	v_pk_mul_f32 v[66:67], v[118:119], v[76:77] op_sel_hi:[0,1]
	v_pk_mul_f32 v[68:69], v[118:119], v[74:75] op_sel_hi:[0,1]
	s_waitcnt vmcnt(0)
	v_pk_fma_f32 v[54:55], v[54:55], v[64:65], v[58:59]
	v_pk_fma_f32 v[56:57], v[56:57], v[62:63], v[60:61]
	global_store_dwordx4 v[120:121], v[54:57], off offset:3072
	global_load_dwordx4 v[54:57], v[4:5], off
	s_nop 0
	global_load_dwordx4 v[58:61], v[6:7], off
	v_pk_mul_f32 v[62:63], v[118:119], v[80:81] op_sel_hi:[0,1]
	v_pk_mul_f32 v[64:65], v[118:119], v[78:79] op_sel_hi:[0,1]
	s_waitcnt vmcnt(0)
	v_pk_fma_f32 v[56:57], v[56:57], v[62:63], v[60:61]
	v_add_co_u32_e32 v62, vcc, s0, v120
	v_pk_fma_f32 v[54:55], v[54:55], v[64:65], v[58:59]
	s_nop 0
	v_addc_co_u32_e32 v63, vcc, 0, v121, vcc
	v_add_co_u32_e32 v64, vcc, s15, v120
	s_movk_i32 s0, 0x3000
	s_nop 0
	v_addc_co_u32_e32 v65, vcc, 0, v121, vcc
	global_store_dwordx4 v[64:65], v[54:57], off offset:-4096
	global_load_dwordx4 v[54:57], v[8:9], off
	s_nop 0
	global_load_dwordx4 v[58:61], v[10:11], off
	s_waitcnt vmcnt(0)
	v_pk_fma_f32 v[54:55], v[54:55], v[68:69], v[58:59]
	v_pk_fma_f32 v[56:57], v[56:57], v[66:67], v[60:61]
	global_store_dwordx4 v[62:63], v[54:57], off offset:1024
	global_load_dwordx4 v[54:57], v[12:13], off
	s_nop 0
	global_load_dwordx4 v[58:61], v[14:15], off
	v_pk_mul_f32 v[66:67], v[118:119], v[72:73] op_sel_hi:[0,1]
	v_pk_mul_f32 v[68:69], v[118:119], v[70:71] op_sel_hi:[0,1]
	s_waitcnt vmcnt(0)
	v_pk_fma_f32 v[54:55], v[54:55], v[68:69], v[58:59]
	v_pk_fma_f32 v[56:57], v[56:57], v[66:67], v[60:61]
	global_store_dwordx4 v[62:63], v[54:57], off offset:2048
	global_load_dwordx4 v[54:57], v[16:17], off
	s_nop 0
	global_load_dwordx4 v[58:61], v[18:19], off
	v_pk_mul_f32 v[66:67], v[118:119], v[84:85] op_sel_hi:[0,1]
	v_pk_mul_f32 v[68:69], v[118:119], v[82:83] op_sel_hi:[0,1]
	s_waitcnt vmcnt(0)
	v_pk_fma_f32 v[54:55], v[54:55], v[68:69], v[58:59]
	v_pk_fma_f32 v[56:57], v[56:57], v[66:67], v[60:61]
	global_store_dwordx4 v[62:63], v[54:57], off offset:3072
	global_load_dwordx4 v[54:57], v[20:21], off
	s_nop 0
	global_load_dwordx4 v[58:61], v[22:23], off
	v_pk_mul_f32 v[62:63], v[118:119], v[88:89] op_sel_hi:[0,1]
	v_pk_mul_f32 v[66:67], v[118:119], v[86:87] op_sel_hi:[0,1]
	s_waitcnt vmcnt(0)
	v_pk_fma_f32 v[54:55], v[54:55], v[66:67], v[58:59]
	v_pk_fma_f32 v[56:57], v[56:57], v[62:63], v[60:61]
	global_store_dwordx4 v[64:65], v[54:57], off
	global_load_dwordx4 v[54:57], v[24:25], off
	s_nop 0
	global_load_dwordx4 v[58:61], v[26:27], off
	v_pk_mul_f32 v[62:63], v[118:119], v[92:93] op_sel_hi:[0,1]
	v_pk_mul_f32 v[66:67], v[118:119], v[90:91] op_sel_hi:[0,1]
	s_waitcnt vmcnt(0)
	v_pk_fma_f32 v[54:55], v[54:55], v[66:67], v[58:59]
	v_pk_fma_f32 v[56:57], v[56:57], v[62:63], v[60:61]
	global_store_dwordx4 v[64:65], v[54:57], off offset:1024
	global_load_dwordx4 v[54:57], v[28:29], off
	s_nop 0
	global_load_dwordx4 v[58:61], v[30:31], off
	v_pk_mul_f32 v[62:63], v[118:119], v[96:97] op_sel_hi:[0,1]
	v_pk_mul_f32 v[66:67], v[118:119], v[94:95] op_sel_hi:[0,1]
	s_waitcnt vmcnt(0)
; __device__ __forceinline__ unsigned pk2(float lo, float hi) { return f2bf(lo) | (f2bf(hi) << 16); }
; __global__ void __launch_bounds__(NWAVES * 64, 2) mega_fwd(Args args) {
;     ...
;                 *(f32x4*)(yr + 4 * lane + 256 * j) = v[j] * rstd * gg + bb; }
;             if (g == 0) {
;                 const float* xs = args.in[1] + (size_t)row * DM;
; #pragma unroll
;                 for (int jb = 0; jb < 4; ++jb) { f32x4 t[4];
; #pragma unroll
;                     for (int j = 0; j < 4; ++j) t[j] = *(const f32x4*)(xs + 4 * lane + 256 * (4 * jb + j));
; #pragma unroll
;                     for (int j = 0; j < 4; ++j) { v2u w; w.x = pk2(t[j][0], t[j][1]); w.y = pk2(t[j][2], t[j][3]); *(v2u*)(XB + (size_t)row * DM + 4 * lane + 256 * (4 * jb + j)) = w; } }
	v_pk_fma_f32 v[54:55], v[54:55], v[66:67], v[58:59]
	v_pk_fma_f32 v[56:57], v[56:57], v[62:63], v[60:61]
	global_store_dwordx4 v[64:65], v[54:57], off offset:2048
	global_load_dwordx4 v[54:57], v[32:33], off
	s_nop 0
	global_load_dwordx4 v[58:61], v[34:35], off
	v_pk_mul_f32 v[62:63], v[118:119], v[100:101] op_sel_hi:[0,1]
	v_pk_mul_f32 v[66:67], v[118:119], v[98:99] op_sel_hi:[0,1]
	s_waitcnt vmcnt(0)
	v_pk_fma_f32 v[54:55], v[54:55], v[66:67], v[58:59]
	v_pk_fma_f32 v[56:57], v[56:57], v[62:63], v[60:61]
	global_store_dwordx4 v[64:65], v[54:57], off offset:3072
	global_load_dwordx4 v[54:57], v[36:37], off
	s_nop 0
	global_load_dwordx4 v[58:61], v[38:39], off
	v_pk_mul_f32 v[62:63], v[118:119], v[104:105] op_sel_hi:[0,1]
	v_pk_mul_f32 v[64:65], v[118:119], v[102:103] op_sel_hi:[0,1]
	v_pk_mul_f32 v[66:67], v[118:119], v[106:107] op_sel_hi:[0,1]
	s_waitcnt vmcnt(0)
	v_pk_fma_f32 v[56:57], v[56:57], v[62:63], v[60:61]
	v_add_co_u32_e32 v62, vcc, s0, v120
	v_pk_fma_f32 v[54:55], v[54:55], v[64:65], v[58:59]
	s_nop 0
	v_addc_co_u32_e32 v63, vcc, 0, v121, vcc
	global_store_dwordx4 v[62:63], v[54:57], off
	global_load_dwordx4 v[54:57], v[40:41], off
	s_nop 0
	global_load_dwordx4 v[58:61], v[42:43], off
	v_pk_mul_f32 v[64:65], v[118:119], v[108:109] op_sel_hi:[0,1]
	s_andn2_b64 vcc, exec, s[4:5]
	s_waitcnt vmcnt(0)
	v_pk_fma_f32 v[54:55], v[54:55], v[66:67], v[58:59]
	v_pk_fma_f32 v[56:57], v[56:57], v[64:65], v[60:61]
	global_store_dwordx4 v[62:63], v[54:57], off offset:1024
	global_load_dwordx4 v[54:57], v[44:45], off
	s_nop 0
	global_load_dwordx4 v[58:61], v[46:47], off
	v_pk_mul_f32 v[64:65], v[118:119], v[112:113] op_sel_hi:[0,1]
	v_pk_mul_f32 v[66:67], v[118:119], v[110:111] op_sel_hi:[0,1]
	s_waitcnt vmcnt(0)
	v_pk_fma_f32 v[54:55], v[54:55], v[66:67], v[58:59]
	v_pk_fma_f32 v[56:57], v[56:57], v[64:65], v[60:61]
	global_store_dwordx4 v[62:63], v[54:57], off offset:2048
	global_load_dwordx4 v[54:57], v[48:49], off
	s_nop 0
	global_load_dwordx4 v[58:61], v[50:51], off
	v_pk_mul_f32 v[64:65], v[118:119], v[114:115] op_sel_hi:[0,1]
	v_pk_mul_f32 v[66:67], v[118:119], v[116:117] op_sel_hi:[0,1]
	s_waitcnt vmcnt(0)
	v_pk_fma_f32 v[54:55], v[54:55], v[66:67], v[58:59]
	v_pk_fma_f32 v[56:57], v[56:57], v[64:65], v[60:61]
	global_store_dwordx4 v[62:63], v[54:57], off offset:3072
	s_cbranch_vccnz .LBB0_661
	s_nop 0
	v_lshl_add_u64 v[54:55], s[40:41], 0, v[192:193]
	global_load_dwordx4 v[56:59], v[54:55], off
	global_load_dwordx4 v[60:63], v[54:55], off offset:1024
	global_load_dwordx4 v[64:67], v[54:55], off offset:2048
	global_load_dwordx4 v[68:71], v[54:55], off offset:3072
	s_mov_b32 s4, 0xdfffe200
	s_mov_b32 s5, -1
	v_lshl_add_u64 v[72:73], v[52:53], 0, s[4:5]
	s_mov_b32 s4, 0xdfffe400
	s_mov_b32 s5, -1
	v_lshl_add_u64 v[74:75], v[52:53], 0, s[4:5]
	s_mov_b32 s4, 0xdfffe600
	s_mov_b32 s5, -1
	v_lshl_add_u64 v[76:77], v[52:53], 0, s[4:5]
	s_mov_b32 s4, 0xdfffe800
	v_add_co_u32_e32 v80, vcc, s15, v54
	s_mov_b32 s5, -1
	s_nop 0
	v_addc_co_u32_e32 v81, vcc, 0, v55, vcc
	s_movk_i32 s0, 0x1000
	v_lshl_add_u64 v[78:79], v[52:53], 0, s[4:5]
	s_mov_b32 s4, 0xdfffea00
	s_mov_b32 s5, -1
	s_waitcnt vmcnt(3)
	v_bfe_u32 v82, v56, 16, 1
	v_bfe_u32 v84, v58, 16, 1
	v_bfe_u32 v83, v57, 16, 1
	v_bfe_u32 v85, v59, 16, 1
	s_waitcnt vmcnt(2)
	v_bfe_u32 v86, v60, 16, 1
	v_bfe_u32 v88, v62, 16, 1
	s_waitcnt vmcnt(1)
	v_bfe_u32 v90, v64, 16, 1
	v_bfe_u32 v92, v66, 16, 1
	s_waitcnt vmcnt(0)
	v_bfe_u32 v94, v68, 16, 1
	v_bfe_u32 v96, v70, 16, 1
	v_add3_u32 v56, v56, v82, s33
	v_add3_u32 v58, v58, v84, s33
	v_bfe_u32 v87, v61, 16, 1
	v_bfe_u32 v89, v63, 16, 1
	v_bfe_u32 v91, v65, 16, 1
	v_bfe_u32 v93, v67, 16, 1
	v_bfe_u32 v95, v69, 16, 1
	v_bfe_u32 v97, v71, 16, 1
	v_add3_u32 v57, v57, v83, s33
	v_add3_u32 v59, v59, v85, s33
	v_add3_u32 v60, v60, v86, s33
	v_add3_u32 v62, v62, v88, s33
	v_add3_u32 v64, v64, v90, s33
	v_add3_u32 v66, v66, v92, s33
	v_add3_u32 v68, v68, v94, s33
	v_add3_u32 v70, v70, v96, s33
	v_lshrrev_b32_e32 v56, 16, v56
	v_lshrrev_b32_e32 v58, 16, v58
	v_add3_u32 v61, v61, v87, s33
	v_add3_u32 v63, v63, v89, s33
	v_add3_u32 v65, v65, v91, s33
	v_add3_u32 v67, v67, v93, s33
	v_add3_u32 v69, v69, v95, s33
	v_add3_u32 v71, v71, v97, s33
	v_lshrrev_b32_e32 v60, 16, v60
	v_lshrrev_b32_e32 v62, 16, v62
	v_lshrrev_b32_e32 v64, 16, v64
	v_lshrrev_b32_e32 v66, 16, v66
	v_lshrrev_b32_e32 v68, 16, v68
	v_lshrrev_b32_e32 v70, 16, v70
	v_and_or_b32 v56, v57, s54, v56
	v_and_or_b32 v57, v59, s54, v58
	v_and_or_b32 v58, v61, s54, v60
	v_and_or_b32 v59, v63, s54, v62
	v_and_or_b32 v60, v65, s54, v64
	v_and_or_b32 v61, v67, s54, v66
	v_and_or_b32 v62, v69, s54, v68
	v_and_or_b32 v63, v71, s54, v70
	global_store_dwordx2 v[72:73], v[56:57], off
	global_store_dwordx2 v[74:75], v[58:59], off
	global_store_dwordx2 v[76:77], v[60:61], off
	global_store_dwordx2 v[78:79], v[62:63], off
	v_add_co_u32_e32 v68, vcc, s0, v54
	global_load_dwordx4 v[56:59], v[80:81], off offset:-4096
	s_nop 0
	v_addc_co_u32_e32 v69, vcc, 0, v55, vcc
	global_load_dwordx4 v[60:63], v[68:69], off offset:1024
	global_load_dwordx4 v[64:67], v[68:69], off offset:2048
	s_nop 0
	global_load_dwordx4 v[68:71], v[68:69], off offset:3072
	v_lshl_add_u64 v[72:73], v[52:53], 0, s[4:5]
	s_mov_b32 s4, 0xdfffec00
	s_mov_b32 s5, -1
	v_lshl_add_u64 v[74:75], v[52:53], 0, s[4:5]
	s_mov_b32 s4, 0xdfffee00
	s_mov_b32 s5, -1
	v_lshl_add_u64 v[76:77], v[52:53], 0, s[4:5]
	s_mov_b32 s4, 0xdffff000
	s_mov_b32 s5, -1
	v_lshl_add_u64 v[78:79], v[52:53], 0, s[4:5]
	s_mov_b32 s4, 0xdffff200
	s_mov_b32 s5, -1
	s_movk_i32 s0, 0x3000
	s_waitcnt vmcnt(3)
	v_bfe_u32 v82, v56, 16, 1
	v_bfe_u32 v84, v58, 16, 1
	v_bfe_u32 v83, v57, 16, 1
	v_bfe_u32 v85, v59, 16, 1
	s_waitcnt vmcnt(2)
; __device__ __forceinline__ unsigned pk2(float lo, float hi) { return f2bf(lo) | (f2bf(hi) << 16); }
; __global__ void __launch_bounds__(NWAVES * 64, 2) mega_fwd(Args args) {
;     ...
;                 for (int jb = 0; jb < 4; ++jb) { f32x4 t[4];
; #pragma unroll
;                     for (int j = 0; j < 4; ++j) t[j] = *(const f32x4*)(xs + 4 * lane + 256 * (4 * jb + j));
; #pragma unroll
;                     for (int j = 0; j < 4; ++j) { v2u w; w.x = pk2(t[j][0], t[j][1]); w.y = pk2(t[j][2], t[j][3]); *(v2u*)(XB + (size_t)row * DM + 4 * lane + 256 * (4 * jb + j)) = w; } }
	v_bfe_u32 v86, v60, 16, 1
	v_bfe_u32 v88, v62, 16, 1
	s_waitcnt vmcnt(1)
	v_bfe_u32 v90, v64, 16, 1
	v_bfe_u32 v92, v66, 16, 1
	s_waitcnt vmcnt(0)
	v_bfe_u32 v94, v68, 16, 1
	v_bfe_u32 v96, v70, 16, 1
	v_add3_u32 v56, v56, v82, s33
	v_add3_u32 v58, v58, v84, s33
	v_bfe_u32 v87, v61, 16, 1
	v_bfe_u32 v89, v63, 16, 1
	v_bfe_u32 v91, v65, 16, 1
	v_bfe_u32 v93, v67, 16, 1
	v_bfe_u32 v95, v69, 16, 1
	v_bfe_u32 v97, v71, 16, 1
	v_add3_u32 v57, v57, v83, s33
	v_add3_u32 v59, v59, v85, s33
	v_add3_u32 v60, v60, v86, s33
	v_add3_u32 v62, v62, v88, s33
	v_add3_u32 v64, v64, v90, s33
	v_add3_u32 v66, v66, v92, s33
	v_add3_u32 v68, v68, v94, s33
	v_add3_u32 v70, v70, v96, s33
	v_lshrrev_b32_e32 v56, 16, v56
	v_lshrrev_b32_e32 v58, 16, v58
	v_add3_u32 v61, v61, v87, s33
	v_add3_u32 v63, v63, v89, s33
	v_add3_u32 v65, v65, v91, s33
	v_add3_u32 v67, v67, v93, s33
	v_add3_u32 v69, v69, v95, s33
	v_add3_u32 v71, v71, v97, s33
	v_lshrrev_b32_e32 v60, 16, v60
	v_lshrrev_b32_e32 v62, 16, v62
	v_lshrrev_b32_e32 v64, 16, v64
	v_lshrrev_b32_e32 v66, 16, v66
	v_lshrrev_b32_e32 v68, 16, v68
	v_lshrrev_b32_e32 v70, 16, v70
	v_and_or_b32 v56, v57, s54, v56
	v_and_or_b32 v57, v59, s54, v58
	v_and_or_b32 v58, v61, s54, v60
	v_and_or_b32 v59, v63, s54, v62
	v_and_or_b32 v60, v65, s54, v64
	v_and_or_b32 v61, v67, s54, v66
	v_and_or_b32 v62, v69, s54, v68
	v_and_or_b32 v63, v71, s54, v70
	global_store_dwordx2 v[72:73], v[56:57], off
	global_store_dwordx2 v[74:75], v[58:59], off
	global_store_dwordx2 v[76:77], v[60:61], off
	global_store_dwordx2 v[78:79], v[62:63], off
	global_load_dwordx4 v[56:59], v[80:81], off
	s_nop 0
	global_load_dwordx4 v[60:63], v[80:81], off offset:1024
	global_load_dwordx4 v[64:67], v[80:81], off offset:2048
	global_load_dwordx4 v[68:71], v[80:81], off offset:3072
	v_lshl_add_u64 v[72:73], v[52:53], 0, s[4:5]
	s_mov_b32 s4, 0xdffff400
	s_mov_b32 s5, -1
	v_lshl_add_u64 v[74:75], v[52:53], 0, s[4:5]
	s_mov_b32 s4, 0xdffff600
	v_add_co_u32_e32 v80, vcc, s0, v54
	s_mov_b32 s5, -1
	s_nop 0
	v_addc_co_u32_e32 v81, vcc, 0, v55, vcc
	v_lshl_add_u64 v[76:77], v[52:53], 0, s[4:5]
	s_mov_b32 s4, 0xdffff800
	s_mov_b32 s5, -1
	v_lshl_add_u64 v[78:79], v[52:53], 0, s[4:5]
	s_mov_b32 s4, 0xdffffa00
	s_mov_b32 s5, -1
	s_waitcnt vmcnt(3)
	v_bfe_u32 v54, v56, 16, 1
	v_bfe_u32 v82, v58, 16, 1
	v_bfe_u32 v55, v57, 16, 1
	v_bfe_u32 v83, v59, 16, 1
	s_waitcnt vmcnt(2)
	v_bfe_u32 v84, v60, 16, 1
	v_bfe_u32 v86, v62, 16, 1
	s_waitcnt vmcnt(1)
	v_bfe_u32 v88, v64, 16, 1
	v_bfe_u32 v90, v66, 16, 1
	s_waitcnt vmcnt(0)
	v_bfe_u32 v92, v68, 16, 1
	v_bfe_u32 v94, v70, 16, 1
	v_add3_u32 v54, v56, v54, s33
	v_add3_u32 v56, v58, v82, s33
	v_bfe_u32 v85, v61, 16, 1
	v_bfe_u32 v87, v63, 16, 1
	v_bfe_u32 v89, v65, 16, 1
	v_bfe_u32 v91, v67, 16, 1
	v_bfe_u32 v93, v69, 16, 1
	v_bfe_u32 v95, v71, 16, 1
	v_add3_u32 v55, v57, v55, s33
	v_add3_u32 v57, v59, v83, s33
	v_add3_u32 v58, v60, v84, s33
	v_add3_u32 v60, v62, v86, s33
	v_add3_u32 v62, v64, v88, s33
	v_add3_u32 v64, v66, v90, s33
	v_add3_u32 v66, v68, v92, s33
	v_add3_u32 v68, v70, v94, s33
	v_lshrrev_b32_e32 v54, 16, v54
	v_lshrrev_b32_e32 v56, 16, v56
	v_add3_u32 v59, v61, v85, s33
	v_add3_u32 v61, v63, v87, s33
	v_add3_u32 v63, v65, v89, s33
	v_add3_u32 v65, v67, v91, s33
	v_add3_u32 v67, v69, v93, s33
	v_add3_u32 v69, v71, v95, s33
	v_lshrrev_b32_e32 v58, 16, v58
	v_lshrrev_b32_e32 v60, 16, v60
	v_lshrrev_b32_e32 v62, 16, v62
	v_lshrrev_b32_e32 v64, 16, v64
	v_lshrrev_b32_e32 v66, 16, v66
	v_lshrrev_b32_e32 v68, 16, v68
	v_and_or_b32 v54, v55, s54, v54
	v_and_or_b32 v55, v57, s54, v56
	v_and_or_b32 v56, v59, s54, v58
	v_and_or_b32 v57, v61, s54, v60
	v_and_or_b32 v58, v63, s54, v62
	v_and_or_b32 v59, v65, s54, v64
	v_and_or_b32 v60, v67, s54, v66
	v_and_or_b32 v61, v69, s54, v68
	global_store_dwordx2 v[72:73], v[54:55], off
	global_store_dwordx2 v[74:75], v[56:57], off
	global_store_dwordx2 v[76:77], v[58:59], off
	global_store_dwordx2 v[78:79], v[60:61], off
	global_load_dwordx4 v[54:57], v[80:81], off
	s_nop 0
	global_load_dwordx4 v[58:61], v[80:81], off offset:1024
	global_load_dwordx4 v[62:65], v[80:81], off offset:2048
	global_load_dwordx4 v[66:69], v[80:81], off offset:3072
	v_lshl_add_u64 v[70:71], v[52:53], 0, s[4:5]
	s_mov_b32 s4, 0xdffffc00
	s_mov_b32 s5, -1
	v_lshl_add_u64 v[72:73], v[52:53], 0, s[4:5]
	s_mov_b32 s4, 0xdffffe00
	s_mov_b32 s5, -1
	v_lshl_add_u64 v[74:75], v[52:53], 0, s[4:5]
	s_brev_b32 s4, 7
	s_mov_b32 s5, -1
	v_lshl_add_u64 v[76:77], v[52:53], 0, s[4:5]
	s_waitcnt vmcnt(3)
	v_bfe_u32 v78, v54, 16, 1
	v_bfe_u32 v80, v56, 16, 1
	v_bfe_u32 v79, v55, 16, 1
	v_bfe_u32 v81, v57, 16, 1
	s_waitcnt vmcnt(2)
	v_bfe_u32 v82, v58, 16, 1
	v_bfe_u32 v84, v60, 16, 1
	s_waitcnt vmcnt(1)
	v_bfe_u32 v86, v62, 16, 1
	v_bfe_u32 v88, v64, 16, 1
	s_waitcnt vmcnt(0)
	v_bfe_u32 v90, v66, 16, 1
	v_bfe_u32 v92, v68, 16, 1
	v_add3_u32 v54, v54, v78, s33
	v_add3_u32 v56, v56, v80, s33
	v_bfe_u32 v83, v59, 16, 1
	v_bfe_u32 v85, v61, 16, 1
	v_bfe_u32 v87, v63, 16, 1
	v_bfe_u32 v89, v65, 16, 1
	v_bfe_u32 v91, v67, 16, 1
	v_bfe_u32 v93, v69, 16, 1
	v_add3_u32 v55, v55, v79, s33
	v_add3_u32 v57, v57, v81, s33
	v_add3_u32 v58, v58, v82, s33
	v_add3_u32 v60, v60, v84, s33
	v_add3_u32 v62, v62, v86, s33
	v_add3_u32 v64, v64, v88, s33
	v_add3_u32 v66, v66, v90, s33
	v_add3_u32 v68, v68, v92, s33
	v_lshrrev_b32_e32 v54, 16, v54
	v_lshrrev_b32_e32 v56, 16, v56
	v_add3_u32 v59, v59, v83, s33
	v_add3_u32 v61, v61, v85, s33
	v_add3_u32 v63, v63, v87, s33
	v_add3_u32 v65, v65, v89, s33
	v_add3_u32 v67, v67, v91, s33
	v_add3_u32 v69, v69, v93, s33
	v_lshrrev_b32_e32 v58, 16, v58
	v_lshrrev_b32_e32 v60, 16, v60
	v_lshrrev_b32_e32 v62, 16, v62
	v_lshrrev_b32_e32 v64, 16, v64
	v_lshrrev_b32_e32 v66, 16, v66
	v_lshrrev_b32_e32 v68, 16, v68
	v_and_or_b32 v54, v55, s54, v54
	v_and_or_b32 v55, v57, s54, v56
	v_and_or_b32 v56, v59, s54, v58
	v_and_or_b32 v57, v61, s54, v60
	v_and_or_b32 v58, v63, s54, v62
	v_and_or_b32 v59, v65, s54, v64
	v_and_or_b32 v60, v67, s54, v66
	v_and_or_b32 v61, v69, s54, v68
	global_store_dwordx2 v[70:71], v[54:55], off
	global_store_dwordx2 v[72:73], v[56:57], off
	global_store_dwordx2 v[74:75], v[58:59], off
	global_store_dwordx2 v[76:77], v[60:61], off
	s_branch .LBB0_661
